# GEMM MFMA phase tail: barrier signalled right after the last MFMA, s_setprio 0 moved behind it
# baseline (speedup 1.0000x reference)
; #define PG8_STAGE(bufoff, gbase, voff) do { _Pragma("unroll") for (int _i = 0; _i < 2; ++_i) \
;         __builtin_amdgcn_global_load_lds((const unsigned*)((const char*)(gbase) + (voff)[_i]), (LAS unsigned*)(lds + (bufoff) + ldsw + _i * 8192), 16, 0, 0); } while (0)
; #define PG8_LDA(dst, b, h) do { _Pragma("unroll") for (int m = 0; m < 4; ++m) _Pragma("unroll") for (int k = 0; k < 2; ++k) dst[m][k] = *(const LAS bf16x8*)(lds + PG8_SA(b, h) + aoff + m * 2048 + k * 1024); } while (0)
; #define PG8_LDB(dst, b, h) do { _Pragma("unroll") for (int n = 0; n < 2; ++n) _Pragma("unroll") for (int k = 0; k < 2; ++k) dst[n][k] = *(const LAS bf16x8*)(lds + PG8_SB(b, h) + boff + n * 2048 + k * 1024); } while (0)
; #define PG8_MMA(ai, bj, At, Bt) do { __builtin_amdgcn_s_setprio(1); _Pragma("unroll") for (int m = 0; m < 4; ++m) _Pragma("unroll") for (int n = 0; n < 2; ++n) _Pragma("unroll") for (int k = 0; k < 2; ++k) \
;         acc[ai][bj][m][n] = __builtin_amdgcn_mfma_f32_16x16x32_bf16(Bt[n][k], At[m][k], acc[ai][bj][m][n], 0, 0, 0); __builtin_amdgcn_s_setprio(0); } while (0)
; #define PG8_WAIT_V(n) asm volatile("s_waitcnt vmcnt(" #n ")" ::: "memory")
; #define PG8_WAIT_L(n) asm volatile("s_waitcnt lgkmcnt(" #n ")" ::: "memory")
; #define PG8_BAR __builtin_amdgcn_s_barrier()
; #define PG8_SCHED __builtin_amdgcn_sched_barrier(0)
; template <class Epi, class Sched, bool ALIGN_EPI = false, bool SP2 = false>
; __device__ __forceinline__ void gemm_phase(LAS unsigned char* lds, const Gemm g, const Sched& S, const Epi& E) {
;     ...
;             const bool last = (t == nt - 2);
;             const char* a1 = cA + (size_t)(t + 1) * kstep;
;             const char* a2 = last ? nA : cA + (size_t)(t + 2) * kstep; const char* b2 = last ? nB : cB + (size_t)(t + 2) * kstep;
;             const char* a3 = a2 + kstep; const char* b3 = b2 + kstep;
;             if (last && has_next) S.a_ready(nxt);
;             if constexpr (SP2) {
;             PG8_LDB(B0, 0, 0); PG8_LDB(B1, 0, 1); PG8_SCHED; PG8_LDA(At, 0, 0); PG8_STAGE(PG8_SA(1, 1), a1 + hstep, voffA);
;             PG8_WAIT_V(8); PG8_WAIT_L(0); PG8_BAR; PG8_MMA(0, 0, At, B0); PG8_MMA(0, 1, At, B1); PG8_BAR; PG8_SCHED;
;             PG8_LDA(At, 0, 1); PG8_STAGE(PG8_SB(0, 0), b2, voffB); PG8_STAGE(PG8_SB(0, 1), b2 + hstep, voffB); PG8_STAGE(PG8_SA(0, 0), a2, voffA);
.LBB0_173:
	s_add_u32 s26, s24, 0xfff80080
	s_addc_u32 s27, s25, -1
	s_add_i32 s45, 0, 0x10000
	s_cmp_eq_u32 s44, 28
	s_cselect_b32 s29, s7, s27
	s_cselect_b32 s28, s8, s26
	v_add_u32_e32 v140, s45, v145
	s_cselect_b32 s27, s17, s43
	s_cselect_b32 s26, s19, s35
	s_add_i32 s47, 0, 0x14000
	ds_read_b128 v[150:153], v140
	ds_read_b128 v[154:157], v140 offset:1024
	ds_read_b128 v[158:161], v140 offset:2048
	ds_read_b128 v[162:165], v140 offset:3072
	v_add_u32_e32 v140, s47, v145
	ds_read_b128 v[166:169], v140
	ds_read_b128 v[170:173], v140 offset:1024
	ds_read_b128 v[174:177], v140 offset:2048
	ds_read_b128 v[178:181], v140 offset:3072
	v_lshl_add_u64 v[140:141], s[24:25], 0, v[136:137]
	s_add_i32 m0, s30, 0xc000
	ds_read_b128 v[182:185], v149
	ds_read_b128 v[194:197], v149 offset:1024
	ds_read_b128 v[198:201], v149 offset:2048
	ds_read_b128 v[202:205], v149 offset:3072
	ds_read_b128 v[206:209], v149 offset:4096
	ds_read_b128 v[210:213], v149 offset:5120
	ds_read_b128 v[214:217], v149 offset:6144
	ds_read_b128 v[218:221], v149 offset:7168
	global_load_lds_dwordx4 v[140:141], off
	v_lshl_add_u64 v[140:141], s[24:25], 0, v[138:139]
	s_add_i32 m0, s30, 0xe000
	s_nop 0
	global_load_lds_dwordx4 v[140:141], off
	s_waitcnt vmcnt(8)
	s_waitcnt lgkmcnt(0)
	s_setprio 1
	s_barrier
	v_mfma_f32_16x16x32_bf16 v[126:129], v[150:153], v[182:185], v[126:129]
	v_mfma_f32_16x16x32_bf16 v[126:129], v[154:157], v[194:197], v[126:129]
	v_mfma_f32_16x16x32_bf16 v[122:125], v[158:161], v[182:185], v[122:125]
	v_mfma_f32_16x16x32_bf16 v[122:125], v[162:165], v[194:197], v[122:125]
	v_mfma_f32_16x16x32_bf16 v[106:109], v[158:161], v[198:201], v[106:109]
	v_mfma_f32_16x16x32_bf16 v[106:109], v[162:165], v[202:205], v[106:109]
	v_mfma_f32_16x16x32_bf16 v[110:113], v[150:153], v[198:201], v[110:113]
	v_mfma_f32_16x16x32_bf16 v[110:113], v[154:157], v[202:205], v[110:113]
	v_mfma_f32_16x16x32_bf16 v[94:97], v[150:153], v[206:209], v[94:97]
	v_mfma_f32_16x16x32_bf16 v[94:97], v[154:157], v[210:213], v[94:97]
	v_mfma_f32_16x16x32_bf16 v[90:93], v[158:161], v[206:209], v[90:93]
	v_mfma_f32_16x16x32_bf16 v[90:93], v[162:165], v[210:213], v[90:93]
	v_mfma_f32_16x16x32_bf16 v[74:77], v[158:161], v[214:217], v[74:77]
	v_mfma_f32_16x16x32_bf16 v[74:77], v[162:165], v[218:221], v[74:77]
	v_mfma_f32_16x16x32_bf16 v[78:81], v[150:153], v[214:217], v[78:81]
	v_mfma_f32_16x16x32_bf16 v[78:81], v[154:157], v[218:221], v[78:81]
	v_mfma_f32_16x16x32_bf16 v[118:121], v[166:169], v[182:185], v[118:121]
	v_mfma_f32_16x16x32_bf16 v[118:121], v[170:173], v[194:197], v[118:121]
	v_mfma_f32_16x16x32_bf16 v[114:117], v[174:177], v[182:185], v[114:117]
	v_mfma_f32_16x16x32_bf16 v[114:117], v[178:181], v[194:197], v[114:117]
	v_mfma_f32_16x16x32_bf16 v[98:101], v[174:177], v[198:201], v[98:101]
	v_mfma_f32_16x16x32_bf16 v[98:101], v[178:181], v[202:205], v[98:101]
	v_mfma_f32_16x16x32_bf16 v[102:105], v[166:169], v[198:201], v[102:105]
	v_mfma_f32_16x16x32_bf16 v[102:105], v[170:173], v[202:205], v[102:105]
	v_mfma_f32_16x16x32_bf16 v[86:89], v[166:169], v[206:209], v[86:89]
	v_mfma_f32_16x16x32_bf16 v[86:89], v[170:173], v[210:213], v[86:89]
	v_mfma_f32_16x16x32_bf16 v[82:85], v[174:177], v[206:209], v[82:85]
	v_mfma_f32_16x16x32_bf16 v[82:85], v[178:181], v[210:213], v[82:85]
	v_mfma_f32_16x16x32_bf16 v[66:69], v[174:177], v[214:217], v[66:69]
	v_mfma_f32_16x16x32_bf16 v[66:69], v[178:181], v[218:221], v[66:69]
	v_mfma_f32_16x16x32_bf16 v[70:73], v[166:169], v[214:217], v[70:73]
	v_mfma_f32_16x16x32_bf16 v[70:73], v[170:173], v[218:221], v[70:73]
	s_barrier
	s_setprio 0
	s_add_i32 s45, s45, s9
	v_lshl_add_u64 v[140:141], s[26:27], 0, v[0:1]
	s_mov_b32 m0, s45
	ds_read_b128 v[182:185], v149 offset:16384
	ds_read_b128 v[194:197], v149 offset:17408
	ds_read_b128 v[198:201], v149 offset:18432
	ds_read_b128 v[202:205], v149 offset:19456
	ds_read_b128 v[206:209], v149 offset:20480
	ds_read_b128 v[210:213], v149 offset:21504
	ds_read_b128 v[214:217], v149 offset:22528
	ds_read_b128 v[218:221], v149 offset:23552
	global_load_lds_dwordx4 v[140:141], off
	s_add_i32 m0, s45, 0x2000
	s_add_u32 s48, s26, 0x80000
	v_lshl_add_u64 v[186:187], s[26:27], 0, v[130:131]
	s_addc_u32 s49, s27, 0
	s_add_i32 s45, s47, s9
	global_load_lds_dwordx4 v[186:187], off
	v_lshl_add_u64 v[188:189], s[48:49], 0, v[0:1]
	s_mov_b32 m0, s45
	v_lshl_add_u64 v[190:191], s[28:29], 0, v[132:133]
	global_load_lds_dwordx4 v[188:189], off
	v_lshl_add_u64 v[188:189], s[48:49], 0, v[130:131]
	s_add_i32 m0, s45, 0x2000
	s_nop 0
	global_load_lds_dwordx4 v[188:189], off
	v_lshl_add_u64 v[188:189], s[28:29], 0, v[134:135]
	s_mov_b32 m0, s30
	s_nop 0
	global_load_lds_dwordx4 v[188:189], off
	s_mov_b32 m0, s31
	s_nop 0
	global_load_lds_dwordx4 v[190:191], off
	s_waitcnt vmcnt(8)
	s_waitcnt lgkmcnt(0)
	s_setprio 1
	s_barrier
; #define PG8_STAGE(bufoff, gbase, voff) do { _Pragma("unroll") for (int _i = 0; _i < 2; ++_i) \
;         __builtin_amdgcn_global_load_lds((const unsigned*)((const char*)(gbase) + (voff)[_i]), (LAS unsigned*)(lds + (bufoff) + ldsw + _i * 8192), 16, 0, 0); } while (0)
; #define PG8_LDA(dst, b, h) do { _Pragma("unroll") for (int m = 0; m < 4; ++m) _Pragma("unroll") for (int k = 0; k < 2; ++k) dst[m][k] = *(const LAS bf16x8*)(lds + PG8_SA(b, h) + aoff + m * 2048 + k * 1024); } while (0)
; #define PG8_LDB(dst, b, h) do { _Pragma("unroll") for (int n = 0; n < 2; ++n) _Pragma("unroll") for (int k = 0; k < 2; ++k) dst[n][k] = *(const LAS bf16x8*)(lds + PG8_SB(b, h) + boff + n * 2048 + k * 1024); } while (0)
; #define PG8_MMA(ai, bj, At, Bt) do { __builtin_amdgcn_s_setprio(1); _Pragma("unroll") for (int m = 0; m < 4; ++m) _Pragma("unroll") for (int n = 0; n < 2; ++n) _Pragma("unroll") for (int k = 0; k < 2; ++k) \
;         acc[ai][bj][m][n] = __builtin_amdgcn_mfma_f32_16x16x32_bf16(Bt[n][k], At[m][k], acc[ai][bj][m][n], 0, 0, 0); __builtin_amdgcn_s_setprio(0); } while (0)
; #define PG8_WAIT_V(n) asm volatile("s_waitcnt vmcnt(" #n ")" ::: "memory")
; #define PG8_WAIT_L(n) asm volatile("s_waitcnt lgkmcnt(" #n ")" ::: "memory")
; #define PG8_BAR __builtin_amdgcn_s_barrier()
; #define PG8_SCHED __builtin_amdgcn_sched_barrier(0)
; template <class Epi, class Sched, bool ALIGN_EPI = false, bool SP2 = false>
; __device__ __forceinline__ void gemm_phase(LAS unsigned char* lds, const Gemm g, const Sched& S, const Epi& E) {
;     ...
;             PG8_WAIT_V(8); PG8_WAIT_L(0); PG8_BAR; PG8_MMA(1, 0, At, B0); PG8_MMA(1, 1, At, B1); PG8_BAR; PG8_SCHED;
;             PG8_LDB(B0, 1, 0); PG8_LDB(B1, 1, 1); PG8_SCHED; PG8_LDA(At, 1, 0); PG8_STAGE(PG8_SA(0, 1), a2 + hstep, voffA);
;             PG8_WAIT_V(8); PG8_WAIT_L(0); PG8_BAR; PG8_MMA(0, 0, At, B0); PG8_MMA(0, 1, At, B1); PG8_BAR; PG8_SCHED;
	v_mfma_f32_16x16x32_bf16 v[62:65], v[150:153], v[182:185], v[62:65]
	v_mfma_f32_16x16x32_bf16 v[62:65], v[154:157], v[194:197], v[62:65]
	v_mfma_f32_16x16x32_bf16 v[58:61], v[158:161], v[182:185], v[58:61]
	v_mfma_f32_16x16x32_bf16 v[58:61], v[162:165], v[194:197], v[58:61]
	v_mfma_f32_16x16x32_bf16 v[42:45], v[158:161], v[198:201], v[42:45]
	v_mfma_f32_16x16x32_bf16 v[42:45], v[162:165], v[202:205], v[42:45]
	v_mfma_f32_16x16x32_bf16 v[46:49], v[150:153], v[198:201], v[46:49]
	v_mfma_f32_16x16x32_bf16 v[46:49], v[154:157], v[202:205], v[46:49]
	v_mfma_f32_16x16x32_bf16 v[30:33], v[150:153], v[206:209], v[30:33]
	v_mfma_f32_16x16x32_bf16 v[30:33], v[154:157], v[210:213], v[30:33]
	v_mfma_f32_16x16x32_bf16 v[26:29], v[158:161], v[206:209], v[26:29]
	v_mfma_f32_16x16x32_bf16 v[26:29], v[162:165], v[210:213], v[26:29]
	v_mfma_f32_16x16x32_bf16 v[10:13], v[158:161], v[214:217], v[10:13]
	v_mfma_f32_16x16x32_bf16 v[10:13], v[162:165], v[218:221], v[10:13]
	v_mfma_f32_16x16x32_bf16 v[14:17], v[150:153], v[214:217], v[14:17]
	v_mfma_f32_16x16x32_bf16 v[14:17], v[154:157], v[218:221], v[14:17]
	v_mfma_f32_16x16x32_bf16 v[54:57], v[166:169], v[182:185], v[54:57]
	v_mfma_f32_16x16x32_bf16 v[54:57], v[170:173], v[194:197], v[54:57]
	v_mfma_f32_16x16x32_bf16 v[50:53], v[174:177], v[182:185], v[50:53]
	v_mfma_f32_16x16x32_bf16 v[50:53], v[178:181], v[194:197], v[50:53]
	v_mfma_f32_16x16x32_bf16 v[34:37], v[174:177], v[198:201], v[34:37]
	v_mfma_f32_16x16x32_bf16 v[34:37], v[178:181], v[202:205], v[34:37]
	v_mfma_f32_16x16x32_bf16 v[38:41], v[166:169], v[198:201], v[38:41]
	v_mfma_f32_16x16x32_bf16 v[38:41], v[170:173], v[202:205], v[38:41]
	v_mfma_f32_16x16x32_bf16 v[22:25], v[166:169], v[206:209], v[22:25]
	v_mfma_f32_16x16x32_bf16 v[22:25], v[170:173], v[210:213], v[22:25]
	v_mfma_f32_16x16x32_bf16 v[18:21], v[174:177], v[206:209], v[18:21]
	v_mfma_f32_16x16x32_bf16 v[18:21], v[178:181], v[210:213], v[18:21]
	v_mfma_f32_16x16x32_bf16 v[2:5], v[174:177], v[214:217], v[2:5]
	v_mfma_f32_16x16x32_bf16 v[2:5], v[178:181], v[218:221], v[2:5]
	v_mfma_f32_16x16x32_bf16 v[6:9], v[166:169], v[214:217], v[6:9]
	v_mfma_f32_16x16x32_bf16 v[6:9], v[170:173], v[218:221], v[6:9]
	s_barrier
	s_setprio 0
	s_add_i32 s45, 0, 0x18000
	v_add_u32_e32 v142, s45, v145
	s_add_i32 s47, 0, 0x1c000
	ds_read_b128 v[150:153], v142
	ds_read_b128 v[154:157], v142 offset:1024
	ds_read_b128 v[158:161], v142 offset:2048
	ds_read_b128 v[162:165], v142 offset:3072
	v_add_u32_e32 v142, s47, v145
	ds_read_b128 v[166:169], v142
	ds_read_b128 v[170:173], v142 offset:1024
	ds_read_b128 v[174:177], v142 offset:2048
	ds_read_b128 v[178:181], v142 offset:3072
	s_add_u32 s28, s28, 0x80000
	s_addc_u32 s29, s29, 0
	s_mov_b32 m0, s38
	v_lshl_add_u64 v[192:193], s[28:29], 0, v[134:135]
	ds_read_b128 v[182:185], v149 offset:32768
	ds_read_b128 v[194:197], v149 offset:33792
	ds_read_b128 v[198:201], v149 offset:34816
	ds_read_b128 v[202:205], v149 offset:35840
	ds_read_b128 v[206:209], v149 offset:36864
	ds_read_b128 v[210:213], v149 offset:37888
	ds_read_b128 v[214:217], v149 offset:38912
	ds_read_b128 v[218:221], v149 offset:39936
	global_load_lds_dwordx4 v[192:193], off
	v_lshl_add_u64 v[192:193], s[28:29], 0, v[132:133]
	s_mov_b32 m0, s39
	s_nop 0
	global_load_lds_dwordx4 v[192:193], off
	s_waitcnt vmcnt(8)
	s_waitcnt lgkmcnt(0)
	s_setprio 1
	s_barrier
	v_mfma_f32_16x16x32_bf16 v[126:129], v[150:153], v[182:185], v[126:129]
	v_mfma_f32_16x16x32_bf16 v[126:129], v[154:157], v[194:197], v[126:129]
	v_mfma_f32_16x16x32_bf16 v[122:125], v[158:161], v[182:185], v[122:125]
	v_mfma_f32_16x16x32_bf16 v[122:125], v[162:165], v[194:197], v[122:125]
	v_mfma_f32_16x16x32_bf16 v[106:109], v[158:161], v[198:201], v[106:109]
	v_mfma_f32_16x16x32_bf16 v[106:109], v[162:165], v[202:205], v[106:109]
	v_mfma_f32_16x16x32_bf16 v[110:113], v[150:153], v[198:201], v[110:113]
	v_mfma_f32_16x16x32_bf16 v[110:113], v[154:157], v[202:205], v[110:113]
	v_mfma_f32_16x16x32_bf16 v[94:97], v[150:153], v[206:209], v[94:97]
	v_mfma_f32_16x16x32_bf16 v[94:97], v[154:157], v[210:213], v[94:97]
	v_mfma_f32_16x16x32_bf16 v[90:93], v[158:161], v[206:209], v[90:93]
	v_mfma_f32_16x16x32_bf16 v[90:93], v[162:165], v[210:213], v[90:93]
	v_mfma_f32_16x16x32_bf16 v[74:77], v[158:161], v[214:217], v[74:77]
	v_mfma_f32_16x16x32_bf16 v[74:77], v[162:165], v[218:221], v[74:77]
	v_mfma_f32_16x16x32_bf16 v[78:81], v[150:153], v[214:217], v[78:81]
	v_mfma_f32_16x16x32_bf16 v[78:81], v[154:157], v[218:221], v[78:81]
	v_mfma_f32_16x16x32_bf16 v[118:121], v[166:169], v[182:185], v[118:121]
	v_mfma_f32_16x16x32_bf16 v[118:121], v[170:173], v[194:197], v[118:121]
	v_mfma_f32_16x16x32_bf16 v[114:117], v[174:177], v[182:185], v[114:117]
	v_mfma_f32_16x16x32_bf16 v[114:117], v[178:181], v[194:197], v[114:117]
	v_mfma_f32_16x16x32_bf16 v[98:101], v[174:177], v[198:201], v[98:101]
	v_mfma_f32_16x16x32_bf16 v[98:101], v[178:181], v[202:205], v[98:101]
	v_mfma_f32_16x16x32_bf16 v[102:105], v[166:169], v[198:201], v[102:105]
	v_mfma_f32_16x16x32_bf16 v[102:105], v[170:173], v[202:205], v[102:105]
	v_mfma_f32_16x16x32_bf16 v[86:89], v[166:169], v[206:209], v[86:89]
	v_mfma_f32_16x16x32_bf16 v[86:89], v[170:173], v[210:213], v[86:89]
	v_mfma_f32_16x16x32_bf16 v[82:85], v[174:177], v[206:209], v[82:85]
	v_mfma_f32_16x16x32_bf16 v[82:85], v[178:181], v[210:213], v[82:85]
	v_mfma_f32_16x16x32_bf16 v[66:69], v[174:177], v[214:217], v[66:69]
	v_mfma_f32_16x16x32_bf16 v[66:69], v[178:181], v[218:221], v[66:69]
	v_mfma_f32_16x16x32_bf16 v[70:73], v[166:169], v[214:217], v[70:73]
	v_mfma_f32_16x16x32_bf16 v[70:73], v[170:173], v[218:221], v[70:73]
	s_barrier
; #define PG8_STAGE(bufoff, gbase, voff) do { _Pragma("unroll") for (int _i = 0; _i < 2; ++_i) \
;         __builtin_amdgcn_global_load_lds((const unsigned*)((const char*)(gbase) + (voff)[_i]), (LAS unsigned*)(lds + (bufoff) + ldsw + _i * 8192), 16, 0, 0); } while (0)
; #define PG8_LDA(dst, b, h) do { _Pragma("unroll") for (int m = 0; m < 4; ++m) _Pragma("unroll") for (int k = 0; k < 2; ++k) dst[m][k] = *(const LAS bf16x8*)(lds + PG8_SA(b, h) + aoff + m * 2048 + k * 1024); } while (0)
; #define PG8_MMA(ai, bj, At, Bt) do { __builtin_amdgcn_s_setprio(1); _Pragma("unroll") for (int m = 0; m < 4; ++m) _Pragma("unroll") for (int n = 0; n < 2; ++n) _Pragma("unroll") for (int k = 0; k < 2; ++k) \
;         acc[ai][bj][m][n] = __builtin_amdgcn_mfma_f32_16x16x32_bf16(Bt[n][k], At[m][k], acc[ai][bj][m][n], 0, 0, 0); __builtin_amdgcn_s_setprio(0); } while (0)
; #define PG8_WAIT_V(n) asm volatile("s_waitcnt vmcnt(" #n ")" ::: "memory")
; #define PG8_WAIT_L(n) asm volatile("s_waitcnt lgkmcnt(" #n ")" ::: "memory")
; #define PG8_BAR __builtin_amdgcn_s_barrier()
; #define PG8_SCHED __builtin_amdgcn_sched_barrier(0)
; template <class Epi, class Sched, bool ALIGN_EPI = false, bool SP2 = false>
; __device__ __forceinline__ void gemm_phase(LAS unsigned char* lds, const Gemm g, const Sched& S, const Epi& E) {
;     ...
;             PG8_WAIT_V(8); PG8_WAIT_L(0); PG8_BAR; PG8_MMA(0, 0, At, B0); PG8_MMA(0, 1, At, B1); PG8_BAR; PG8_SCHED;
;             PG8_LDA(At, 1, 1); PG8_STAGE(PG8_SB(1, 0), b3, voffB); PG8_STAGE(PG8_SB(1, 1), b3 + hstep, voffB); PG8_STAGE(PG8_SA(1, 0), a3, voffA);
;             PG8_WAIT_V(8); PG8_WAIT_L(0); PG8_BAR; PG8_MMA(1, 0, At, B0); PG8_MMA(1, 1, At, B1); PG8_BAR; PG8_SCHED;
;     ...
;         if constexpr (ALIGN_EPI) { if (wr == 0) PG8_BAR; }
	s_setprio 0
	s_add_i32 s28, s45, s9
	v_lshl_add_u64 v[140:141], v[140:141], 0, s[12:13]
	s_mov_b32 m0, s28
	ds_read_b128 v[182:185], v149 offset:49152
	ds_read_b128 v[194:197], v149 offset:50176
	ds_read_b128 v[198:201], v149 offset:51200
	ds_read_b128 v[202:205], v149 offset:52224
	ds_read_b128 v[206:209], v149 offset:53248
	ds_read_b128 v[210:213], v149 offset:54272
	ds_read_b128 v[214:217], v149 offset:55296
	ds_read_b128 v[218:221], v149 offset:56320
	global_load_lds_dwordx4 v[140:141], off
	s_add_i32 m0, s28, 0x2000
	s_add_u32 s26, s26, 0x80080
	v_lshl_add_u64 v[140:141], v[186:187], 0, s[12:13]
	s_addc_u32 s27, s27, 0
	s_add_i32 s28, s47, s9
	global_load_lds_dwordx4 v[140:141], off
	v_lshl_add_u64 v[140:141], s[26:27], 0, v[0:1]
	s_mov_b32 m0, s28
	s_nop 0
	global_load_lds_dwordx4 v[140:141], off
	v_lshl_add_u64 v[140:141], s[26:27], 0, v[130:131]
	s_add_i32 m0, s28, 0x2000
	s_nop 0
	global_load_lds_dwordx4 v[140:141], off
	v_lshl_add_u64 v[140:141], v[188:189], 0, s[12:13]
	s_mov_b32 m0, s40
	s_nop 0
	global_load_lds_dwordx4 v[140:141], off
	v_lshl_add_u64 v[140:141], v[190:191], 0, s[12:13]
	s_mov_b32 m0, s41
	s_nop 0
	global_load_lds_dwordx4 v[140:141], off
	s_waitcnt vmcnt(8)
	s_waitcnt lgkmcnt(0)
	s_setprio 1
	s_barrier
	v_mfma_f32_16x16x32_bf16 v[62:65], v[150:153], v[182:185], v[62:65]
	v_mfma_f32_16x16x32_bf16 v[62:65], v[154:157], v[194:197], v[62:65]
	v_mfma_f32_16x16x32_bf16 v[58:61], v[158:161], v[182:185], v[58:61]
	v_mfma_f32_16x16x32_bf16 v[58:61], v[162:165], v[194:197], v[58:61]
	v_mfma_f32_16x16x32_bf16 v[42:45], v[158:161], v[198:201], v[42:45]
	v_mfma_f32_16x16x32_bf16 v[42:45], v[162:165], v[202:205], v[42:45]
	v_mfma_f32_16x16x32_bf16 v[46:49], v[150:153], v[198:201], v[46:49]
	v_mfma_f32_16x16x32_bf16 v[46:49], v[154:157], v[202:205], v[46:49]
	v_mfma_f32_16x16x32_bf16 v[30:33], v[150:153], v[206:209], v[30:33]
	v_mfma_f32_16x16x32_bf16 v[30:33], v[154:157], v[210:213], v[30:33]
	v_mfma_f32_16x16x32_bf16 v[26:29], v[158:161], v[206:209], v[26:29]
	v_mfma_f32_16x16x32_bf16 v[26:29], v[162:165], v[210:213], v[26:29]
	v_mfma_f32_16x16x32_bf16 v[10:13], v[158:161], v[214:217], v[10:13]
	v_mfma_f32_16x16x32_bf16 v[10:13], v[162:165], v[218:221], v[10:13]
	v_mfma_f32_16x16x32_bf16 v[14:17], v[150:153], v[214:217], v[14:17]
	v_mfma_f32_16x16x32_bf16 v[14:17], v[154:157], v[218:221], v[14:17]
	v_mfma_f32_16x16x32_bf16 v[54:57], v[166:169], v[182:185], v[54:57]
	v_mfma_f32_16x16x32_bf16 v[54:57], v[170:173], v[194:197], v[54:57]
	v_mfma_f32_16x16x32_bf16 v[50:53], v[174:177], v[182:185], v[50:53]
	v_mfma_f32_16x16x32_bf16 v[50:53], v[178:181], v[194:197], v[50:53]
	v_mfma_f32_16x16x32_bf16 v[34:37], v[174:177], v[198:201], v[34:37]
	v_mfma_f32_16x16x32_bf16 v[34:37], v[178:181], v[202:205], v[34:37]
	v_mfma_f32_16x16x32_bf16 v[38:41], v[166:169], v[198:201], v[38:41]
	v_mfma_f32_16x16x32_bf16 v[38:41], v[170:173], v[202:205], v[38:41]
	v_mfma_f32_16x16x32_bf16 v[22:25], v[166:169], v[206:209], v[22:25]
	v_mfma_f32_16x16x32_bf16 v[22:25], v[170:173], v[210:213], v[22:25]
	v_mfma_f32_16x16x32_bf16 v[18:21], v[174:177], v[206:209], v[18:21]
	v_mfma_f32_16x16x32_bf16 v[18:21], v[178:181], v[210:213], v[18:21]
	v_mfma_f32_16x16x32_bf16 v[2:5], v[174:177], v[214:217], v[2:5]
	v_mfma_f32_16x16x32_bf16 v[2:5], v[178:181], v[218:221], v[2:5]
	v_mfma_f32_16x16x32_bf16 v[6:9], v[166:169], v[214:217], v[6:9]
	v_mfma_f32_16x16x32_bf16 v[6:9], v[170:173], v[218:221], v[6:9]
	s_barrier
	s_setprio 0
	s_add_i32 s44, s44, 2
	s_add_u32 s24, s24, 0x100
	s_addc_u32 s25, s25, 0
	s_add_u32 s35, s35, 0x100
	s_addc_u32 s43, s43, 0
	s_cmp_gt_u32 s44, 29
	s_cbranch_scc0 .LBB0_173
	s_and_b64 vcc, exec, s[4:5]
	s_cbranch_vccz .LBB0_176
	s_barrier

; #define PG8_STAGE(bufoff, gbase, voff) do { _Pragma("unroll") for (int _i = 0; _i < 2; ++_i) \
;         __builtin_amdgcn_global_load_lds((const unsigned*)((const char*)(gbase) + (voff)[_i]), (LAS unsigned*)(lds + (bufoff) + ldsw + _i * 8192), 16, 0, 0); } while (0)
; #define PG8_LDA(dst, b, h) do { _Pragma("unroll") for (int m = 0; m < 4; ++m) _Pragma("unroll") for (int k = 0; k < 2; ++k) dst[m][k] = *(const LAS bf16x8*)(lds + PG8_SA(b, h) + aoff + m * 2048 + k * 1024); } while (0)
; #define PG8_LDB(dst, b, h) do { _Pragma("unroll") for (int n = 0; n < 2; ++n) _Pragma("unroll") for (int k = 0; k < 2; ++k) dst[n][k] = *(const LAS bf16x8*)(lds + PG8_SB(b, h) + boff + n * 2048 + k * 1024); } while (0)
; #define PG8_MMA(ai, bj, At, Bt) do { __builtin_amdgcn_s_setprio(1); _Pragma("unroll") for (int m = 0; m < 4; ++m) _Pragma("unroll") for (int n = 0; n < 2; ++n) _Pragma("unroll") for (int k = 0; k < 2; ++k) \
;         acc[ai][bj][m][n] = __builtin_amdgcn_mfma_f32_16x16x32_bf16(Bt[n][k], At[m][k], acc[ai][bj][m][n], 0, 0, 0); __builtin_amdgcn_s_setprio(0); } while (0)
; #define PG8_WAIT_V(n) asm volatile("s_waitcnt vmcnt(" #n ")" ::: "memory")
; #define PG8_WAIT_L(n) asm volatile("s_waitcnt lgkmcnt(" #n ")" ::: "memory")
; #define PG8_BAR __builtin_amdgcn_s_barrier()
; #define PG8_SCHED __builtin_amdgcn_sched_barrier(0)
; template <class Epi, class Sched, bool ALIGN_EPI = false, bool SP2 = false>
; __device__ __forceinline__ void gemm_phase(LAS unsigned char* lds, const Gemm g, const Sched& S, const Epi& E) {
;     ...
;             const bool last = (t == nt - 2);
;             const char* a1 = cA + (size_t)(t + 1) * kstep;
;             const char* a2 = last ? nA : cA + (size_t)(t + 2) * kstep; const char* b2 = last ? nB : cB + (size_t)(t + 2) * kstep;
;             const char* a3 = a2 + kstep; const char* b3 = b2 + kstep;
;             if (last && has_next) S.a_ready(nxt);
;             if constexpr (SP2) {
;             PG8_LDB(B0, 0, 0); PG8_LDB(B1, 0, 1); PG8_SCHED; PG8_LDA(At, 0, 0); PG8_STAGE(PG8_SA(1, 1), a1 + hstep, voffA);
;             PG8_WAIT_V(8); PG8_WAIT_L(0); PG8_BAR; PG8_MMA(0, 0, At, B0); PG8_MMA(0, 1, At, B1); PG8_BAR; PG8_SCHED;
;             PG8_LDA(At, 0, 1); PG8_STAGE(PG8_SB(0, 0), b2, voffB); PG8_STAGE(PG8_SB(0, 1), b2 + hstep, voffB); PG8_STAGE(PG8_SA(0, 0), a2, voffA);
.LBB0_257:
	s_add_u32 s24, s22, 0x100
	s_addc_u32 s25, s23, 0
	s_add_i32 s50, 0, 0x10000
	s_cmpk_eq_i32 s49, 0x54
	s_cselect_b32 s29, s1, s25
	s_cselect_b32 s28, s0, s24
	s_cselect_b32 s27, s21, s48
	s_cselect_b32 s26, s20, s47
	s_add_i32 s51, 0, 0x14000
	v_add_u32_e32 v126, s50, v247
	v_add_u32_e32 v158, s51, v247
	ds_read_b128 v[90:93], v126
	ds_read_b128 v[102:105], v126 offset:1024
	ds_read_b128 v[114:117], v126 offset:2048
	ds_read_b128 v[126:129], v126 offset:3072
	ds_read_b128 v[138:141], v158
	ds_read_b128 v[142:145], v158 offset:1024
	ds_read_b128 v[154:157], v158 offset:2048
	ds_read_b128 v[158:161], v158 offset:3072
	v_lshl_add_u64 v[186:187], s[22:23], 0, v[200:201]
	s_add_i32 m0, s6, 0xc000
	ds_read_b128 v[162:165], v249
	ds_read_b128 v[166:169], v249 offset:1024
	ds_read_b128 v[170:173], v249 offset:2048
	ds_read_b128 v[174:177], v249 offset:3072
	ds_read_b128 v[178:181], v249 offset:4096
	ds_read_b128 v[182:185], v249 offset:5120
	ds_read_b128 v[204:207], v249 offset:6144
	ds_read_b128 v[208:211], v249 offset:7168
	global_load_lds_dwordx4 v[186:187], off
	v_lshl_add_u64 v[186:187], s[22:23], 0, v[202:203]
	s_add_i32 m0, s6, 0xe000
	s_nop 0
	global_load_lds_dwordx4 v[186:187], off
	s_waitcnt vmcnt(8)
	s_waitcnt lgkmcnt(0)
	s_setprio 1
	s_barrier
	v_mfma_f32_16x16x32_bf16 v[150:153], v[90:93], v[162:165], v[150:153]
	v_mfma_f32_16x16x32_bf16 v[150:153], v[102:105], v[166:169], v[150:153]
	v_mfma_f32_16x16x32_bf16 v[146:149], v[114:117], v[162:165], v[146:149]
	v_mfma_f32_16x16x32_bf16 v[146:149], v[126:129], v[166:169], v[146:149]
	v_mfma_f32_16x16x32_bf16 v[118:121], v[114:117], v[170:173], v[118:121]
	v_mfma_f32_16x16x32_bf16 v[118:121], v[126:129], v[174:177], v[118:121]
	v_mfma_f32_16x16x32_bf16 v[122:125], v[90:93], v[170:173], v[122:125]
	v_mfma_f32_16x16x32_bf16 v[122:125], v[102:105], v[174:177], v[122:125]
	v_mfma_f32_16x16x32_bf16 v[98:101], v[90:93], v[178:181], v[98:101]
	v_mfma_f32_16x16x32_bf16 v[98:101], v[102:105], v[182:185], v[98:101]
	v_mfma_f32_16x16x32_bf16 v[94:97], v[114:117], v[178:181], v[94:97]
	v_mfma_f32_16x16x32_bf16 v[94:97], v[126:129], v[182:185], v[94:97]
	v_mfma_f32_16x16x32_bf16 v[74:77], v[114:117], v[204:207], v[74:77]
	v_mfma_f32_16x16x32_bf16 v[74:77], v[126:129], v[208:211], v[74:77]
	v_mfma_f32_16x16x32_bf16 v[78:81], v[90:93], v[204:207], v[78:81]
	v_mfma_f32_16x16x32_bf16 v[78:81], v[102:105], v[208:211], v[78:81]
	v_mfma_f32_16x16x32_bf16 v[134:137], v[138:141], v[162:165], v[134:137]
	v_mfma_f32_16x16x32_bf16 v[134:137], v[142:145], v[166:169], v[134:137]
	v_mfma_f32_16x16x32_bf16 v[130:133], v[154:157], v[162:165], v[130:133]
	v_mfma_f32_16x16x32_bf16 v[130:133], v[158:161], v[166:169], v[130:133]
	v_mfma_f32_16x16x32_bf16 v[106:109], v[154:157], v[170:173], v[106:109]
	v_mfma_f32_16x16x32_bf16 v[106:109], v[158:161], v[174:177], v[106:109]
	v_mfma_f32_16x16x32_bf16 v[110:113], v[138:141], v[170:173], v[110:113]
	v_mfma_f32_16x16x32_bf16 v[110:113], v[142:145], v[174:177], v[110:113]
	v_mfma_f32_16x16x32_bf16 v[86:89], v[138:141], v[178:181], v[86:89]
	v_mfma_f32_16x16x32_bf16 v[86:89], v[142:145], v[182:185], v[86:89]
	v_mfma_f32_16x16x32_bf16 v[82:85], v[154:157], v[178:181], v[82:85]
	v_mfma_f32_16x16x32_bf16 v[82:85], v[158:161], v[182:185], v[82:85]
	v_mfma_f32_16x16x32_bf16 v[66:69], v[154:157], v[204:207], v[66:69]
	v_mfma_f32_16x16x32_bf16 v[66:69], v[158:161], v[208:211], v[66:69]
	v_mfma_f32_16x16x32_bf16 v[70:73], v[138:141], v[204:207], v[70:73]
	v_mfma_f32_16x16x32_bf16 v[70:73], v[142:145], v[208:211], v[70:73]
	s_barrier
	s_setprio 0
	s_add_i32 s22, s50, s2
	v_lshl_add_u64 v[186:187], s[26:27], 0, v[0:1]
	s_mov_b32 m0, s22
	ds_read_b128 v[162:165], v249 offset:16384
	ds_read_b128 v[166:169], v249 offset:17408
	ds_read_b128 v[170:173], v249 offset:18432
	ds_read_b128 v[174:177], v249 offset:19456
	ds_read_b128 v[178:181], v249 offset:20480
	ds_read_b128 v[182:185], v249 offset:21504
	ds_read_b128 v[204:207], v249 offset:22528
	ds_read_b128 v[208:211], v249 offset:23552
	global_load_lds_dwordx4 v[186:187], off
	s_add_i32 m0, s22, 0x2000
	s_add_u32 s22, s26, 0x160000
	v_lshl_add_u64 v[188:189], s[26:27], 0, v[194:195]
	s_addc_u32 s23, s27, 0
	s_add_i32 s50, s51, s2
	global_load_lds_dwordx4 v[188:189], off
	v_lshl_add_u64 v[190:191], s[22:23], 0, v[0:1]
	s_mov_b32 m0, s50
	v_lshl_add_u64 v[192:193], s[28:29], 0, v[196:197]
	global_load_lds_dwordx4 v[190:191], off
	v_lshl_add_u64 v[190:191], s[22:23], 0, v[194:195]
	s_add_i32 m0, s50, 0x2000
	s_nop 0
	global_load_lds_dwordx4 v[190:191], off
	v_lshl_add_u64 v[190:191], s[28:29], 0, v[198:199]
	s_mov_b32 m0, s6
	s_nop 0
	global_load_lds_dwordx4 v[190:191], off
	s_mov_b32 m0, s7
	s_nop 0
	global_load_lds_dwordx4 v[192:193], off
	s_waitcnt vmcnt(8)
	s_waitcnt lgkmcnt(0)
	s_setprio 1
	s_barrier
; #define PG8_STAGE(bufoff, gbase, voff) do { _Pragma("unroll") for (int _i = 0; _i < 2; ++_i) \
;         __builtin_amdgcn_global_load_lds((const unsigned*)((const char*)(gbase) + (voff)[_i]), (LAS unsigned*)(lds + (bufoff) + ldsw + _i * 8192), 16, 0, 0); } while (0)
; #define PG8_LDA(dst, b, h) do { _Pragma("unroll") for (int m = 0; m < 4; ++m) _Pragma("unroll") for (int k = 0; k < 2; ++k) dst[m][k] = *(const LAS bf16x8*)(lds + PG8_SA(b, h) + aoff + m * 2048 + k * 1024); } while (0)
; #define PG8_LDB(dst, b, h) do { _Pragma("unroll") for (int n = 0; n < 2; ++n) _Pragma("unroll") for (int k = 0; k < 2; ++k) dst[n][k] = *(const LAS bf16x8*)(lds + PG8_SB(b, h) + boff + n * 2048 + k * 1024); } while (0)
; #define PG8_MMA(ai, bj, At, Bt) do { __builtin_amdgcn_s_setprio(1); _Pragma("unroll") for (int m = 0; m < 4; ++m) _Pragma("unroll") for (int n = 0; n < 2; ++n) _Pragma("unroll") for (int k = 0; k < 2; ++k) \
;         acc[ai][bj][m][n] = __builtin_amdgcn_mfma_f32_16x16x32_bf16(Bt[n][k], At[m][k], acc[ai][bj][m][n], 0, 0, 0); __builtin_amdgcn_s_setprio(0); } while (0)
; #define PG8_WAIT_V(n) asm volatile("s_waitcnt vmcnt(" #n ")" ::: "memory")
; #define PG8_WAIT_L(n) asm volatile("s_waitcnt lgkmcnt(" #n ")" ::: "memory")
; #define PG8_BAR __builtin_amdgcn_s_barrier()
; #define PG8_SCHED __builtin_amdgcn_sched_barrier(0)
; template <class Epi, class Sched, bool ALIGN_EPI = false, bool SP2 = false>
; __device__ __forceinline__ void gemm_phase(LAS unsigned char* lds, const Gemm g, const Sched& S, const Epi& E) {
;     ...
;             PG8_WAIT_V(8); PG8_WAIT_L(0); PG8_BAR; PG8_MMA(1, 0, At, B0); PG8_MMA(1, 1, At, B1); PG8_BAR; PG8_SCHED;
;             PG8_LDB(B0, 1, 0); PG8_LDB(B1, 1, 1); PG8_SCHED; PG8_LDA(At, 1, 0); PG8_STAGE(PG8_SA(0, 1), a2 + hstep, voffA);
;             PG8_WAIT_V(8); PG8_WAIT_L(0); PG8_BAR; PG8_MMA(0, 0, At, B0); PG8_MMA(0, 1, At, B1); PG8_BAR; PG8_SCHED;
	v_mfma_f32_16x16x32_bf16 v[62:65], v[90:93], v[162:165], v[62:65]
	v_mfma_f32_16x16x32_bf16 v[62:65], v[102:105], v[166:169], v[62:65]
	v_mfma_f32_16x16x32_bf16 v[58:61], v[114:117], v[162:165], v[58:61]
	v_mfma_f32_16x16x32_bf16 v[58:61], v[126:129], v[166:169], v[58:61]
	v_mfma_f32_16x16x32_bf16 v[42:45], v[114:117], v[170:173], v[42:45]
	v_mfma_f32_16x16x32_bf16 v[42:45], v[126:129], v[174:177], v[42:45]
	v_mfma_f32_16x16x32_bf16 v[46:49], v[90:93], v[170:173], v[46:49]
	v_mfma_f32_16x16x32_bf16 v[46:49], v[102:105], v[174:177], v[46:49]
	v_mfma_f32_16x16x32_bf16 v[30:33], v[90:93], v[178:181], v[30:33]
	v_mfma_f32_16x16x32_bf16 v[30:33], v[102:105], v[182:185], v[30:33]
	v_mfma_f32_16x16x32_bf16 v[26:29], v[114:117], v[178:181], v[26:29]
	v_mfma_f32_16x16x32_bf16 v[26:29], v[126:129], v[182:185], v[26:29]
	v_mfma_f32_16x16x32_bf16 v[10:13], v[114:117], v[204:207], v[10:13]
	v_mfma_f32_16x16x32_bf16 v[10:13], v[126:129], v[208:211], v[10:13]
	v_mfma_f32_16x16x32_bf16 v[14:17], v[90:93], v[204:207], v[14:17]
	v_mfma_f32_16x16x32_bf16 v[14:17], v[102:105], v[208:211], v[14:17]
	v_mfma_f32_16x16x32_bf16 v[54:57], v[138:141], v[162:165], v[54:57]
	v_mfma_f32_16x16x32_bf16 v[54:57], v[142:145], v[166:169], v[54:57]
	v_mfma_f32_16x16x32_bf16 v[50:53], v[154:157], v[162:165], v[50:53]
	v_mfma_f32_16x16x32_bf16 v[50:53], v[158:161], v[166:169], v[50:53]
	v_mfma_f32_16x16x32_bf16 v[34:37], v[154:157], v[170:173], v[34:37]
	v_mfma_f32_16x16x32_bf16 v[34:37], v[158:161], v[174:177], v[34:37]
	v_mfma_f32_16x16x32_bf16 v[38:41], v[138:141], v[170:173], v[38:41]
	v_mfma_f32_16x16x32_bf16 v[38:41], v[142:145], v[174:177], v[38:41]
	v_mfma_f32_16x16x32_bf16 v[22:25], v[138:141], v[178:181], v[22:25]
	v_mfma_f32_16x16x32_bf16 v[22:25], v[142:145], v[182:185], v[22:25]
	v_mfma_f32_16x16x32_bf16 v[18:21], v[154:157], v[178:181], v[18:21]
	v_mfma_f32_16x16x32_bf16 v[18:21], v[158:161], v[182:185], v[18:21]
	v_mfma_f32_16x16x32_bf16 v[2:5], v[154:157], v[204:207], v[2:5]
	v_mfma_f32_16x16x32_bf16 v[2:5], v[158:161], v[208:211], v[2:5]
	v_mfma_f32_16x16x32_bf16 v[6:9], v[138:141], v[204:207], v[6:9]
	v_mfma_f32_16x16x32_bf16 v[6:9], v[142:145], v[208:211], v[6:9]
	s_barrier
	s_setprio 0
	s_add_i32 s50, 0, 0x18000
	s_add_i32 s51, 0, 0x1c000
	v_add_u32_e32 v126, s50, v247
	v_add_u32_e32 v158, s51, v247
	ds_read_b128 v[90:93], v126
	ds_read_b128 v[102:105], v126 offset:1024
	ds_read_b128 v[114:117], v126 offset:2048
	ds_read_b128 v[126:129], v126 offset:3072
	ds_read_b128 v[138:141], v158
	ds_read_b128 v[142:145], v158 offset:1024
	ds_read_b128 v[154:157], v158 offset:2048
	ds_read_b128 v[158:161], v158 offset:3072
	s_add_u32 s22, s28, 0x160000
	s_addc_u32 s23, s29, 0
	s_mov_b32 m0, s8
	v_lshl_add_u64 v[212:213], s[22:23], 0, v[198:199]
	ds_read_b128 v[162:165], v249 offset:32768
	ds_read_b128 v[166:169], v249 offset:33792
	ds_read_b128 v[170:173], v249 offset:34816
	ds_read_b128 v[174:177], v249 offset:35840
	ds_read_b128 v[178:181], v249 offset:36864
	ds_read_b128 v[182:185], v249 offset:37888
	ds_read_b128 v[204:207], v249 offset:38912
	ds_read_b128 v[208:211], v249 offset:39936
	global_load_lds_dwordx4 v[212:213], off
	v_lshl_add_u64 v[212:213], s[22:23], 0, v[196:197]
	s_mov_b32 m0, s31
	s_nop 0
	global_load_lds_dwordx4 v[212:213], off
	s_waitcnt vmcnt(8)
	s_waitcnt lgkmcnt(0)
	s_setprio 1
	s_barrier
	v_mfma_f32_16x16x32_bf16 v[150:153], v[90:93], v[162:165], v[150:153]
	v_mfma_f32_16x16x32_bf16 v[150:153], v[102:105], v[166:169], v[150:153]
	v_mfma_f32_16x16x32_bf16 v[146:149], v[114:117], v[162:165], v[146:149]
	v_mfma_f32_16x16x32_bf16 v[146:149], v[126:129], v[166:169], v[146:149]
	v_mfma_f32_16x16x32_bf16 v[118:121], v[114:117], v[170:173], v[118:121]
	v_mfma_f32_16x16x32_bf16 v[118:121], v[126:129], v[174:177], v[118:121]
	v_mfma_f32_16x16x32_bf16 v[122:125], v[90:93], v[170:173], v[122:125]
	v_mfma_f32_16x16x32_bf16 v[122:125], v[102:105], v[174:177], v[122:125]
	v_mfma_f32_16x16x32_bf16 v[98:101], v[90:93], v[178:181], v[98:101]
	v_mfma_f32_16x16x32_bf16 v[98:101], v[102:105], v[182:185], v[98:101]
	v_mfma_f32_16x16x32_bf16 v[94:97], v[114:117], v[178:181], v[94:97]
	v_mfma_f32_16x16x32_bf16 v[94:97], v[126:129], v[182:185], v[94:97]
	v_mfma_f32_16x16x32_bf16 v[74:77], v[114:117], v[204:207], v[74:77]
	v_mfma_f32_16x16x32_bf16 v[74:77], v[126:129], v[208:211], v[74:77]
	v_mfma_f32_16x16x32_bf16 v[78:81], v[90:93], v[204:207], v[78:81]
	v_mfma_f32_16x16x32_bf16 v[78:81], v[102:105], v[208:211], v[78:81]
	v_mfma_f32_16x16x32_bf16 v[134:137], v[138:141], v[162:165], v[134:137]
	v_mfma_f32_16x16x32_bf16 v[134:137], v[142:145], v[166:169], v[134:137]
	v_mfma_f32_16x16x32_bf16 v[130:133], v[154:157], v[162:165], v[130:133]
	v_mfma_f32_16x16x32_bf16 v[130:133], v[158:161], v[166:169], v[130:133]
	v_mfma_f32_16x16x32_bf16 v[106:109], v[154:157], v[170:173], v[106:109]
	v_mfma_f32_16x16x32_bf16 v[106:109], v[158:161], v[174:177], v[106:109]
	v_mfma_f32_16x16x32_bf16 v[110:113], v[138:141], v[170:173], v[110:113]
	v_mfma_f32_16x16x32_bf16 v[110:113], v[142:145], v[174:177], v[110:113]
	v_mfma_f32_16x16x32_bf16 v[86:89], v[138:141], v[178:181], v[86:89]
	v_mfma_f32_16x16x32_bf16 v[86:89], v[142:145], v[182:185], v[86:89]
	v_mfma_f32_16x16x32_bf16 v[82:85], v[154:157], v[178:181], v[82:85]
	v_mfma_f32_16x16x32_bf16 v[82:85], v[158:161], v[182:185], v[82:85]
	v_mfma_f32_16x16x32_bf16 v[66:69], v[154:157], v[204:207], v[66:69]
	v_mfma_f32_16x16x32_bf16 v[66:69], v[158:161], v[208:211], v[66:69]
	v_mfma_f32_16x16x32_bf16 v[70:73], v[138:141], v[204:207], v[70:73]
	v_mfma_f32_16x16x32_bf16 v[70:73], v[142:145], v[208:211], v[70:73]
	s_barrier
; #define PG8_STAGE(bufoff, gbase, voff) do { _Pragma("unroll") for (int _i = 0; _i < 2; ++_i) \
;         __builtin_amdgcn_global_load_lds((const unsigned*)((const char*)(gbase) + (voff)[_i]), (LAS unsigned*)(lds + (bufoff) + ldsw + _i * 8192), 16, 0, 0); } while (0)
; #define PG8_LDA(dst, b, h) do { _Pragma("unroll") for (int m = 0; m < 4; ++m) _Pragma("unroll") for (int k = 0; k < 2; ++k) dst[m][k] = *(const LAS bf16x8*)(lds + PG8_SA(b, h) + aoff + m * 2048 + k * 1024); } while (0)
; #define PG8_MMA(ai, bj, At, Bt) do { __builtin_amdgcn_s_setprio(1); _Pragma("unroll") for (int m = 0; m < 4; ++m) _Pragma("unroll") for (int n = 0; n < 2; ++n) _Pragma("unroll") for (int k = 0; k < 2; ++k) \
;         acc[ai][bj][m][n] = __builtin_amdgcn_mfma_f32_16x16x32_bf16(Bt[n][k], At[m][k], acc[ai][bj][m][n], 0, 0, 0); __builtin_amdgcn_s_setprio(0); } while (0)
; #define PG8_WAIT_V(n) asm volatile("s_waitcnt vmcnt(" #n ")" ::: "memory")
; #define PG8_WAIT_L(n) asm volatile("s_waitcnt lgkmcnt(" #n ")" ::: "memory")
; #define PG8_BAR __builtin_amdgcn_s_barrier()
; #define PG8_SCHED __builtin_amdgcn_sched_barrier(0)
; template <class Epi, class Sched, bool ALIGN_EPI = false, bool SP2 = false>
; __device__ __forceinline__ void gemm_phase(LAS unsigned char* lds, const Gemm g, const Sched& S, const Epi& E) {
;     ...
;             PG8_WAIT_V(8); PG8_WAIT_L(0); PG8_BAR; PG8_MMA(0, 0, At, B0); PG8_MMA(0, 1, At, B1); PG8_BAR; PG8_SCHED;
;             PG8_LDA(At, 1, 1); PG8_STAGE(PG8_SB(1, 0), b3, voffB); PG8_STAGE(PG8_SB(1, 1), b3 + hstep, voffB); PG8_STAGE(PG8_SA(1, 0), a3, voffA);
;             PG8_WAIT_V(8); PG8_WAIT_L(0); PG8_BAR; PG8_MMA(1, 0, At, B0); PG8_MMA(1, 1, At, B1); PG8_BAR; PG8_SCHED;
;     ...
;         if constexpr (ALIGN_EPI) { if (wr == 0) PG8_BAR; }
	s_setprio 0
	s_add_i32 s22, s50, s2
	v_lshl_add_u64 v[186:187], v[186:187], 0, s[12:13]
	s_mov_b32 m0, s22
	ds_read_b128 v[162:165], v249 offset:49152
	ds_read_b128 v[166:169], v249 offset:50176
	ds_read_b128 v[170:173], v249 offset:51200
	ds_read_b128 v[174:177], v249 offset:52224
	ds_read_b128 v[178:181], v249 offset:53248
	ds_read_b128 v[182:185], v249 offset:54272
	ds_read_b128 v[204:207], v249 offset:55296
	ds_read_b128 v[208:211], v249 offset:56320
	global_load_lds_dwordx4 v[186:187], off
	s_add_i32 m0, s22, 0x2000
	s_add_u32 s22, s26, 0x160080
	v_lshl_add_u64 v[186:187], v[188:189], 0, s[12:13]
	s_addc_u32 s23, s27, 0
	s_add_i32 s26, s51, s2
	global_load_lds_dwordx4 v[186:187], off
	v_lshl_add_u64 v[186:187], s[22:23], 0, v[0:1]
	s_mov_b32 m0, s26
	s_nop 0
	global_load_lds_dwordx4 v[186:187], off
	v_lshl_add_u64 v[186:187], s[22:23], 0, v[194:195]
	s_add_i32 m0, s26, 0x2000
	s_nop 0
	global_load_lds_dwordx4 v[186:187], off
	v_lshl_add_u64 v[186:187], v[190:191], 0, s[12:13]
	s_mov_b32 m0, s35
	s_nop 0
	global_load_lds_dwordx4 v[186:187], off
	v_lshl_add_u64 v[186:187], v[192:193], 0, s[12:13]
	s_mov_b32 m0, s40
	s_nop 0
	global_load_lds_dwordx4 v[186:187], off
	s_waitcnt vmcnt(8)
	s_waitcnt lgkmcnt(0)
	s_setprio 1
	s_barrier
	v_mfma_f32_16x16x32_bf16 v[62:65], v[90:93], v[162:165], v[62:65]
	v_mfma_f32_16x16x32_bf16 v[62:65], v[102:105], v[166:169], v[62:65]
	v_mfma_f32_16x16x32_bf16 v[58:61], v[114:117], v[162:165], v[58:61]
	v_mfma_f32_16x16x32_bf16 v[58:61], v[126:129], v[166:169], v[58:61]
	v_mfma_f32_16x16x32_bf16 v[42:45], v[114:117], v[170:173], v[42:45]
	v_mfma_f32_16x16x32_bf16 v[42:45], v[126:129], v[174:177], v[42:45]
	v_mfma_f32_16x16x32_bf16 v[46:49], v[90:93], v[170:173], v[46:49]
	v_mfma_f32_16x16x32_bf16 v[46:49], v[102:105], v[174:177], v[46:49]
	v_mfma_f32_16x16x32_bf16 v[30:33], v[90:93], v[178:181], v[30:33]
	v_mfma_f32_16x16x32_bf16 v[30:33], v[102:105], v[182:185], v[30:33]
	v_mfma_f32_16x16x32_bf16 v[26:29], v[114:117], v[178:181], v[26:29]
	v_mfma_f32_16x16x32_bf16 v[26:29], v[126:129], v[182:185], v[26:29]
	v_mfma_f32_16x16x32_bf16 v[10:13], v[114:117], v[204:207], v[10:13]
	v_mfma_f32_16x16x32_bf16 v[10:13], v[126:129], v[208:211], v[10:13]
	v_mfma_f32_16x16x32_bf16 v[14:17], v[90:93], v[204:207], v[14:17]
	v_mfma_f32_16x16x32_bf16 v[14:17], v[102:105], v[208:211], v[14:17]
	v_mfma_f32_16x16x32_bf16 v[54:57], v[138:141], v[162:165], v[54:57]
	v_mfma_f32_16x16x32_bf16 v[54:57], v[142:145], v[166:169], v[54:57]
	v_mfma_f32_16x16x32_bf16 v[50:53], v[154:157], v[162:165], v[50:53]
	v_mfma_f32_16x16x32_bf16 v[50:53], v[158:161], v[166:169], v[50:53]
	v_mfma_f32_16x16x32_bf16 v[34:37], v[154:157], v[170:173], v[34:37]
	v_mfma_f32_16x16x32_bf16 v[34:37], v[158:161], v[174:177], v[34:37]
	v_mfma_f32_16x16x32_bf16 v[38:41], v[138:141], v[170:173], v[38:41]
	v_mfma_f32_16x16x32_bf16 v[38:41], v[142:145], v[174:177], v[38:41]
	v_mfma_f32_16x16x32_bf16 v[22:25], v[138:141], v[178:181], v[22:25]
	v_mfma_f32_16x16x32_bf16 v[22:25], v[142:145], v[182:185], v[22:25]
	v_mfma_f32_16x16x32_bf16 v[18:21], v[154:157], v[178:181], v[18:21]
	v_mfma_f32_16x16x32_bf16 v[18:21], v[158:161], v[182:185], v[18:21]
	v_mfma_f32_16x16x32_bf16 v[2:5], v[154:157], v[204:207], v[2:5]
	v_mfma_f32_16x16x32_bf16 v[2:5], v[158:161], v[208:211], v[2:5]
	v_mfma_f32_16x16x32_bf16 v[6:9], v[138:141], v[204:207], v[6:9]
	v_mfma_f32_16x16x32_bf16 v[6:9], v[142:145], v[208:211], v[6:9]
	s_barrier
	s_setprio 0
	s_add_i32 s49, s49, 2
	s_add_u32 s47, s47, 0x100
	s_addc_u32 s48, s48, 0
	s_cmpk_gt_u32 s49, 0x55
	s_mov_b64 s[22:23], s[24:25]
	s_cbranch_scc0 .LBB0_257
	s_and_b64 vcc, exec, s[18:19]
	s_cbranch_vccz .LBB0_260
	s_barrier

; #define PG8_STAGE(bufoff, gbase, voff) do { _Pragma("unroll") for (int _i = 0; _i < 2; ++_i) \
;         __builtin_amdgcn_global_load_lds((const unsigned*)((const char*)(gbase) + (voff)[_i]), (LAS unsigned*)(lds + (bufoff) + ldsw + _i * 8192), 16, 0, 0); } while (0)
; #define PG8_LDA(dst, b, h) do { _Pragma("unroll") for (int m = 0; m < 4; ++m) _Pragma("unroll") for (int k = 0; k < 2; ++k) dst[m][k] = *(const LAS bf16x8*)(lds + PG8_SA(b, h) + aoff + m * 2048 + k * 1024); } while (0)
; #define PG8_LDB(dst, b, h) do { _Pragma("unroll") for (int n = 0; n < 2; ++n) _Pragma("unroll") for (int k = 0; k < 2; ++k) dst[n][k] = *(const LAS bf16x8*)(lds + PG8_SB(b, h) + boff + n * 2048 + k * 1024); } while (0)
; #define PG8_MMA(ai, bj, At, Bt) do { __builtin_amdgcn_s_setprio(1); _Pragma("unroll") for (int m = 0; m < 4; ++m) _Pragma("unroll") for (int n = 0; n < 2; ++n) _Pragma("unroll") for (int k = 0; k < 2; ++k) \
;         acc[ai][bj][m][n] = __builtin_amdgcn_mfma_f32_16x16x32_bf16(Bt[n][k], At[m][k], acc[ai][bj][m][n], 0, 0, 0); __builtin_amdgcn_s_setprio(0); } while (0)
; #define PG8_WAIT_V(n) asm volatile("s_waitcnt vmcnt(" #n ")" ::: "memory")
; #define PG8_WAIT_L(n) asm volatile("s_waitcnt lgkmcnt(" #n ")" ::: "memory")
; #define PG8_BAR __builtin_amdgcn_s_barrier()
; #define PG8_SCHED __builtin_amdgcn_sched_barrier(0)
; template <class Epi, class Sched, bool ALIGN_EPI = false, bool SP2 = false>
; __device__ __forceinline__ void gemm_phase(LAS unsigned char* lds, const Gemm g, const Sched& S, const Epi& E) {
;     ...
;             const bool last = (t == nt - 2);
;             const char* a1 = cA + (size_t)(t + 1) * kstep;
;             const char* a2 = last ? nA : cA + (size_t)(t + 2) * kstep; const char* b2 = last ? nB : cB + (size_t)(t + 2) * kstep;
;             const char* a3 = a2 + kstep; const char* b3 = b2 + kstep;
;             if (last && has_next) S.a_ready(nxt);
;             if constexpr (SP2) {
;             PG8_LDB(B0, 0, 0); PG8_LDB(B1, 0, 1); PG8_SCHED; PG8_LDA(At, 0, 0); PG8_STAGE(PG8_SA(1, 1), a1 + hstep, voffA);
;             PG8_WAIT_V(8); PG8_WAIT_L(0); PG8_BAR; PG8_MMA(0, 0, At, B0); PG8_MMA(0, 1, At, B1); PG8_BAR; PG8_SCHED;
;             PG8_LDA(At, 0, 1); PG8_STAGE(PG8_SB(0, 0), b2, voffB); PG8_STAGE(PG8_SB(0, 1), b2 + hstep, voffB); PG8_STAGE(PG8_SA(0, 0), a2, voffA);
.LBB0_359:
	s_add_u32 s28, s26, 0xfff80080
	s_addc_u32 s29, s27, -1
	s_add_i32 s41, 0, 0x10000
	s_cmp_eq_u32 s40, 28
	s_cselect_b32 s31, s6, s29
	s_cselect_b32 s30, s7, s28
	v_add_u32_e32 v0, s41, v159
	s_cselect_b32 s29, s8, s35
	s_cselect_b32 s28, s19, s21
	s_add_i32 s57, 0, 0x14000
	ds_read_b128 v[142:145], v0
	ds_read_b128 v[146:149], v0 offset:1024
	ds_read_b128 v[150:153], v0 offset:2048
	ds_read_b128 v[154:157], v0 offset:3072
	v_add_u32_e32 v0, s57, v159
	ds_read_b128 v[162:165], v0
	ds_read_b128 v[166:169], v0 offset:1024
	ds_read_b128 v[170:173], v0 offset:2048
	ds_read_b128 v[174:177], v0 offset:3072
	v_lshl_add_u64 v[210:211], s[26:27], 0, v[138:139]
	s_add_i32 m0, s44, 0xc000
	ds_read_b128 v[178:181], v161
	ds_read_b128 v[182:185], v161 offset:1024
	ds_read_b128 v[186:189], v161 offset:2048
	ds_read_b128 v[190:193], v161 offset:3072
	ds_read_b128 v[194:197], v161 offset:4096
	ds_read_b128 v[198:201], v161 offset:5120
	ds_read_b128 v[202:205], v161 offset:6144
	ds_read_b128 v[206:209], v161 offset:7168
	global_load_lds_dwordx4 v[210:211], off
	v_lshl_add_u64 v[210:211], s[26:27], 0, v[140:141]
	s_add_i32 m0, s44, 0xe000
	s_nop 0
	global_load_lds_dwordx4 v[210:211], off
	s_waitcnt vmcnt(8)
	s_waitcnt lgkmcnt(0)
	s_setprio 1
	s_barrier
	v_mfma_f32_16x16x32_bf16 v[126:129], v[142:145], v[178:181], v[126:129]
	v_mfma_f32_16x16x32_bf16 v[126:129], v[146:149], v[182:185], v[126:129]
	v_mfma_f32_16x16x32_bf16 v[122:125], v[150:153], v[178:181], v[122:125]
	v_mfma_f32_16x16x32_bf16 v[122:125], v[154:157], v[182:185], v[122:125]
	v_mfma_f32_16x16x32_bf16 v[106:109], v[150:153], v[186:189], v[106:109]
	v_mfma_f32_16x16x32_bf16 v[106:109], v[154:157], v[190:193], v[106:109]
	v_mfma_f32_16x16x32_bf16 v[110:113], v[142:145], v[186:189], v[110:113]
	v_mfma_f32_16x16x32_bf16 v[110:113], v[146:149], v[190:193], v[110:113]
	v_mfma_f32_16x16x32_bf16 v[94:97], v[142:145], v[194:197], v[94:97]
	v_mfma_f32_16x16x32_bf16 v[94:97], v[146:149], v[198:201], v[94:97]
	v_mfma_f32_16x16x32_bf16 v[90:93], v[150:153], v[194:197], v[90:93]
	v_mfma_f32_16x16x32_bf16 v[90:93], v[154:157], v[198:201], v[90:93]
	v_mfma_f32_16x16x32_bf16 v[74:77], v[150:153], v[202:205], v[74:77]
	v_mfma_f32_16x16x32_bf16 v[74:77], v[154:157], v[206:209], v[74:77]
	v_mfma_f32_16x16x32_bf16 v[78:81], v[142:145], v[202:205], v[78:81]
	v_mfma_f32_16x16x32_bf16 v[78:81], v[146:149], v[206:209], v[78:81]
	v_mfma_f32_16x16x32_bf16 v[118:121], v[162:165], v[178:181], v[118:121]
	v_mfma_f32_16x16x32_bf16 v[118:121], v[166:169], v[182:185], v[118:121]
	v_mfma_f32_16x16x32_bf16 v[114:117], v[170:173], v[178:181], v[114:117]
	v_mfma_f32_16x16x32_bf16 v[114:117], v[174:177], v[182:185], v[114:117]
	v_mfma_f32_16x16x32_bf16 v[98:101], v[170:173], v[186:189], v[98:101]
	v_mfma_f32_16x16x32_bf16 v[98:101], v[174:177], v[190:193], v[98:101]
	v_mfma_f32_16x16x32_bf16 v[102:105], v[162:165], v[186:189], v[102:105]
	v_mfma_f32_16x16x32_bf16 v[102:105], v[166:169], v[190:193], v[102:105]
	v_mfma_f32_16x16x32_bf16 v[86:89], v[162:165], v[194:197], v[86:89]
	v_mfma_f32_16x16x32_bf16 v[86:89], v[166:169], v[198:201], v[86:89]
	v_mfma_f32_16x16x32_bf16 v[82:85], v[170:173], v[194:197], v[82:85]
	v_mfma_f32_16x16x32_bf16 v[82:85], v[174:177], v[198:201], v[82:85]
	v_mfma_f32_16x16x32_bf16 v[66:69], v[170:173], v[202:205], v[66:69]
	v_mfma_f32_16x16x32_bf16 v[66:69], v[174:177], v[206:209], v[66:69]
	v_mfma_f32_16x16x32_bf16 v[70:73], v[162:165], v[202:205], v[70:73]
	v_mfma_f32_16x16x32_bf16 v[70:73], v[166:169], v[206:209], v[70:73]
	s_barrier
	s_setprio 0
	s_add_i32 s41, s41, s9
	v_lshl_add_u64 v[210:211], s[28:29], 0, v[134:135]
	s_mov_b32 m0, s41
	ds_read_b128 v[178:181], v161 offset:16384
	ds_read_b128 v[182:185], v161 offset:17408
	ds_read_b128 v[186:189], v161 offset:18432
	ds_read_b128 v[190:193], v161 offset:19456
	ds_read_b128 v[194:197], v161 offset:20480
	ds_read_b128 v[198:201], v161 offset:21504
	ds_read_b128 v[202:205], v161 offset:22528
	ds_read_b128 v[206:209], v161 offset:23552
	global_load_lds_dwordx4 v[210:211], off
	s_add_i32 m0, s41, 0x2000
	s_add_u32 s58, s28, 0x80000
	v_lshl_add_u64 v[212:213], s[28:29], 0, v[130:131]
	s_addc_u32 s59, s29, 0
	s_add_i32 s41, s57, s9
	global_load_lds_dwordx4 v[212:213], off
	v_lshl_add_u64 v[214:215], s[58:59], 0, v[134:135]
	s_mov_b32 m0, s41
	v_lshl_add_u64 v[216:217], s[30:31], 0, v[132:133]
	global_load_lds_dwordx4 v[214:215], off
	v_lshl_add_u64 v[214:215], s[58:59], 0, v[130:131]
	s_add_i32 m0, s41, 0x2000
	s_nop 0
	global_load_lds_dwordx4 v[214:215], off
	v_lshl_add_u64 v[214:215], s[30:31], 0, v[136:137]
	s_mov_b32 m0, s44
	s_nop 0
	global_load_lds_dwordx4 v[214:215], off
	s_mov_b32 m0, s45
	s_nop 0
	global_load_lds_dwordx4 v[216:217], off
	s_waitcnt vmcnt(8)
	s_waitcnt lgkmcnt(0)
	s_setprio 1
	s_barrier
; #define PG8_STAGE(bufoff, gbase, voff) do { _Pragma("unroll") for (int _i = 0; _i < 2; ++_i) \
;         __builtin_amdgcn_global_load_lds((const unsigned*)((const char*)(gbase) + (voff)[_i]), (LAS unsigned*)(lds + (bufoff) + ldsw + _i * 8192), 16, 0, 0); } while (0)
; #define PG8_LDA(dst, b, h) do { _Pragma("unroll") for (int m = 0; m < 4; ++m) _Pragma("unroll") for (int k = 0; k < 2; ++k) dst[m][k] = *(const LAS bf16x8*)(lds + PG8_SA(b, h) + aoff + m * 2048 + k * 1024); } while (0)
; #define PG8_LDB(dst, b, h) do { _Pragma("unroll") for (int n = 0; n < 2; ++n) _Pragma("unroll") for (int k = 0; k < 2; ++k) dst[n][k] = *(const LAS bf16x8*)(lds + PG8_SB(b, h) + boff + n * 2048 + k * 1024); } while (0)
; #define PG8_MMA(ai, bj, At, Bt) do { __builtin_amdgcn_s_setprio(1); _Pragma("unroll") for (int m = 0; m < 4; ++m) _Pragma("unroll") for (int n = 0; n < 2; ++n) _Pragma("unroll") for (int k = 0; k < 2; ++k) \
;         acc[ai][bj][m][n] = __builtin_amdgcn_mfma_f32_16x16x32_bf16(Bt[n][k], At[m][k], acc[ai][bj][m][n], 0, 0, 0); __builtin_amdgcn_s_setprio(0); } while (0)
; #define PG8_WAIT_V(n) asm volatile("s_waitcnt vmcnt(" #n ")" ::: "memory")
; #define PG8_WAIT_L(n) asm volatile("s_waitcnt lgkmcnt(" #n ")" ::: "memory")
; #define PG8_BAR __builtin_amdgcn_s_barrier()
; #define PG8_SCHED __builtin_amdgcn_sched_barrier(0)
; template <class Epi, class Sched, bool ALIGN_EPI = false, bool SP2 = false>
; __device__ __forceinline__ void gemm_phase(LAS unsigned char* lds, const Gemm g, const Sched& S, const Epi& E) {
;     ...
;             PG8_WAIT_V(8); PG8_WAIT_L(0); PG8_BAR; PG8_MMA(1, 0, At, B0); PG8_MMA(1, 1, At, B1); PG8_BAR; PG8_SCHED;
;             PG8_LDB(B0, 1, 0); PG8_LDB(B1, 1, 1); PG8_SCHED; PG8_LDA(At, 1, 0); PG8_STAGE(PG8_SA(0, 1), a2 + hstep, voffA);
;             PG8_WAIT_V(8); PG8_WAIT_L(0); PG8_BAR; PG8_MMA(0, 0, At, B0); PG8_MMA(0, 1, At, B1); PG8_BAR; PG8_SCHED;
	v_mfma_f32_16x16x32_bf16 v[62:65], v[142:145], v[178:181], v[62:65]
	v_mfma_f32_16x16x32_bf16 v[62:65], v[146:149], v[182:185], v[62:65]
	v_mfma_f32_16x16x32_bf16 v[58:61], v[150:153], v[178:181], v[58:61]
	v_mfma_f32_16x16x32_bf16 v[58:61], v[154:157], v[182:185], v[58:61]
	v_mfma_f32_16x16x32_bf16 v[42:45], v[150:153], v[186:189], v[42:45]
	v_mfma_f32_16x16x32_bf16 v[42:45], v[154:157], v[190:193], v[42:45]
	v_mfma_f32_16x16x32_bf16 v[46:49], v[142:145], v[186:189], v[46:49]
	v_mfma_f32_16x16x32_bf16 v[46:49], v[146:149], v[190:193], v[46:49]
	v_mfma_f32_16x16x32_bf16 v[30:33], v[142:145], v[194:197], v[30:33]
	v_mfma_f32_16x16x32_bf16 v[30:33], v[146:149], v[198:201], v[30:33]
	v_mfma_f32_16x16x32_bf16 v[26:29], v[150:153], v[194:197], v[26:29]
	v_mfma_f32_16x16x32_bf16 v[26:29], v[154:157], v[198:201], v[26:29]
	v_mfma_f32_16x16x32_bf16 v[10:13], v[150:153], v[202:205], v[10:13]
	v_mfma_f32_16x16x32_bf16 v[10:13], v[154:157], v[206:209], v[10:13]
	v_mfma_f32_16x16x32_bf16 v[14:17], v[142:145], v[202:205], v[14:17]
	v_mfma_f32_16x16x32_bf16 v[14:17], v[146:149], v[206:209], v[14:17]
	v_mfma_f32_16x16x32_bf16 v[54:57], v[162:165], v[178:181], v[54:57]
	v_mfma_f32_16x16x32_bf16 v[54:57], v[166:169], v[182:185], v[54:57]
	v_mfma_f32_16x16x32_bf16 v[50:53], v[170:173], v[178:181], v[50:53]
	v_mfma_f32_16x16x32_bf16 v[50:53], v[174:177], v[182:185], v[50:53]
	v_mfma_f32_16x16x32_bf16 v[34:37], v[170:173], v[186:189], v[34:37]
	v_mfma_f32_16x16x32_bf16 v[34:37], v[174:177], v[190:193], v[34:37]
	v_mfma_f32_16x16x32_bf16 v[38:41], v[162:165], v[186:189], v[38:41]
	v_mfma_f32_16x16x32_bf16 v[38:41], v[166:169], v[190:193], v[38:41]
	v_mfma_f32_16x16x32_bf16 v[22:25], v[162:165], v[194:197], v[22:25]
	v_mfma_f32_16x16x32_bf16 v[22:25], v[166:169], v[198:201], v[22:25]
	v_mfma_f32_16x16x32_bf16 v[18:21], v[170:173], v[194:197], v[18:21]
	v_mfma_f32_16x16x32_bf16 v[18:21], v[174:177], v[198:201], v[18:21]
	v_mfma_f32_16x16x32_bf16 v[2:5], v[170:173], v[202:205], v[2:5]
	v_mfma_f32_16x16x32_bf16 v[2:5], v[174:177], v[206:209], v[2:5]
	v_mfma_f32_16x16x32_bf16 v[6:9], v[162:165], v[202:205], v[6:9]
	v_mfma_f32_16x16x32_bf16 v[6:9], v[166:169], v[206:209], v[6:9]
	s_barrier
	s_setprio 0
	s_add_i32 s41, 0, 0x18000
	v_add_u32_e32 v0, s41, v159
	s_add_i32 s57, 0, 0x1c000
	ds_read_b128 v[142:145], v0
	ds_read_b128 v[146:149], v0 offset:1024
	ds_read_b128 v[150:153], v0 offset:2048
	ds_read_b128 v[154:157], v0 offset:3072
	v_add_u32_e32 v0, s57, v159
	ds_read_b128 v[162:165], v0
	ds_read_b128 v[166:169], v0 offset:1024
	ds_read_b128 v[170:173], v0 offset:2048
	ds_read_b128 v[174:177], v0 offset:3072
	s_add_u32 s30, s30, 0x80000
	s_addc_u32 s31, s31, 0
	s_mov_b32 m0, s47
	v_lshl_add_u64 v[218:219], s[30:31], 0, v[136:137]
	ds_read_b128 v[178:181], v161 offset:32768
	ds_read_b128 v[182:185], v161 offset:33792
	ds_read_b128 v[186:189], v161 offset:34816
	ds_read_b128 v[190:193], v161 offset:35840
	ds_read_b128 v[194:197], v161 offset:36864
	ds_read_b128 v[198:201], v161 offset:37888
	ds_read_b128 v[202:205], v161 offset:38912
	ds_read_b128 v[206:209], v161 offset:39936
	global_load_lds_dwordx4 v[218:219], off
	v_lshl_add_u64 v[218:219], s[30:31], 0, v[132:133]
	s_mov_b32 m0, s48
	s_nop 0
	global_load_lds_dwordx4 v[218:219], off
	s_waitcnt vmcnt(8)
	s_waitcnt lgkmcnt(0)
	s_setprio 1
	s_barrier
	v_mfma_f32_16x16x32_bf16 v[126:129], v[142:145], v[178:181], v[126:129]
	v_mfma_f32_16x16x32_bf16 v[126:129], v[146:149], v[182:185], v[126:129]
	v_mfma_f32_16x16x32_bf16 v[122:125], v[150:153], v[178:181], v[122:125]
	v_mfma_f32_16x16x32_bf16 v[122:125], v[154:157], v[182:185], v[122:125]
	v_mfma_f32_16x16x32_bf16 v[106:109], v[150:153], v[186:189], v[106:109]
	v_mfma_f32_16x16x32_bf16 v[106:109], v[154:157], v[190:193], v[106:109]
	v_mfma_f32_16x16x32_bf16 v[110:113], v[142:145], v[186:189], v[110:113]
	v_mfma_f32_16x16x32_bf16 v[110:113], v[146:149], v[190:193], v[110:113]
	v_mfma_f32_16x16x32_bf16 v[94:97], v[142:145], v[194:197], v[94:97]
	v_mfma_f32_16x16x32_bf16 v[94:97], v[146:149], v[198:201], v[94:97]
	v_mfma_f32_16x16x32_bf16 v[90:93], v[150:153], v[194:197], v[90:93]
	v_mfma_f32_16x16x32_bf16 v[90:93], v[154:157], v[198:201], v[90:93]
	v_mfma_f32_16x16x32_bf16 v[74:77], v[150:153], v[202:205], v[74:77]
	v_mfma_f32_16x16x32_bf16 v[74:77], v[154:157], v[206:209], v[74:77]
	v_mfma_f32_16x16x32_bf16 v[78:81], v[142:145], v[202:205], v[78:81]
	v_mfma_f32_16x16x32_bf16 v[78:81], v[146:149], v[206:209], v[78:81]
	v_mfma_f32_16x16x32_bf16 v[118:121], v[162:165], v[178:181], v[118:121]
	v_mfma_f32_16x16x32_bf16 v[118:121], v[166:169], v[182:185], v[118:121]
	v_mfma_f32_16x16x32_bf16 v[114:117], v[170:173], v[178:181], v[114:117]
	v_mfma_f32_16x16x32_bf16 v[114:117], v[174:177], v[182:185], v[114:117]
	v_mfma_f32_16x16x32_bf16 v[98:101], v[170:173], v[186:189], v[98:101]
	v_mfma_f32_16x16x32_bf16 v[98:101], v[174:177], v[190:193], v[98:101]
	v_mfma_f32_16x16x32_bf16 v[102:105], v[162:165], v[186:189], v[102:105]
	v_mfma_f32_16x16x32_bf16 v[102:105], v[166:169], v[190:193], v[102:105]
	v_mfma_f32_16x16x32_bf16 v[86:89], v[162:165], v[194:197], v[86:89]
	v_mfma_f32_16x16x32_bf16 v[86:89], v[166:169], v[198:201], v[86:89]
	v_mfma_f32_16x16x32_bf16 v[82:85], v[170:173], v[194:197], v[82:85]
	v_mfma_f32_16x16x32_bf16 v[82:85], v[174:177], v[198:201], v[82:85]
	v_mfma_f32_16x16x32_bf16 v[66:69], v[170:173], v[202:205], v[66:69]
	v_mfma_f32_16x16x32_bf16 v[66:69], v[174:177], v[206:209], v[66:69]
	v_mfma_f32_16x16x32_bf16 v[70:73], v[162:165], v[202:205], v[70:73]
	v_mfma_f32_16x16x32_bf16 v[70:73], v[166:169], v[206:209], v[70:73]
	s_barrier
; #define PG8_STAGE(bufoff, gbase, voff) do { _Pragma("unroll") for (int _i = 0; _i < 2; ++_i) \
;         __builtin_amdgcn_global_load_lds((const unsigned*)((const char*)(gbase) + (voff)[_i]), (LAS unsigned*)(lds + (bufoff) + ldsw + _i * 8192), 16, 0, 0); } while (0)
; #define PG8_LDA(dst, b, h) do { _Pragma("unroll") for (int m = 0; m < 4; ++m) _Pragma("unroll") for (int k = 0; k < 2; ++k) dst[m][k] = *(const LAS bf16x8*)(lds + PG8_SA(b, h) + aoff + m * 2048 + k * 1024); } while (0)
; #define PG8_MMA(ai, bj, At, Bt) do { __builtin_amdgcn_s_setprio(1); _Pragma("unroll") for (int m = 0; m < 4; ++m) _Pragma("unroll") for (int n = 0; n < 2; ++n) _Pragma("unroll") for (int k = 0; k < 2; ++k) \
;         acc[ai][bj][m][n] = __builtin_amdgcn_mfma_f32_16x16x32_bf16(Bt[n][k], At[m][k], acc[ai][bj][m][n], 0, 0, 0); __builtin_amdgcn_s_setprio(0); } while (0)
; #define PG8_WAIT_V(n) asm volatile("s_waitcnt vmcnt(" #n ")" ::: "memory")
; #define PG8_WAIT_L(n) asm volatile("s_waitcnt lgkmcnt(" #n ")" ::: "memory")
; #define PG8_BAR __builtin_amdgcn_s_barrier()
; #define PG8_SCHED __builtin_amdgcn_sched_barrier(0)
; template <class Epi, class Sched, bool ALIGN_EPI = false, bool SP2 = false>
; __device__ __forceinline__ void gemm_phase(LAS unsigned char* lds, const Gemm g, const Sched& S, const Epi& E) {
;     ...
;             PG8_WAIT_V(8); PG8_WAIT_L(0); PG8_BAR; PG8_MMA(0, 0, At, B0); PG8_MMA(0, 1, At, B1); PG8_BAR; PG8_SCHED;
;             PG8_LDA(At, 1, 1); PG8_STAGE(PG8_SB(1, 0), b3, voffB); PG8_STAGE(PG8_SB(1, 1), b3 + hstep, voffB); PG8_STAGE(PG8_SA(1, 0), a3, voffA);
;             PG8_WAIT_V(8); PG8_WAIT_L(0); PG8_BAR; PG8_MMA(1, 0, At, B0); PG8_MMA(1, 1, At, B1); PG8_BAR; PG8_SCHED;
;     ...
;         if constexpr (ALIGN_EPI) { if (wr == 0) PG8_BAR; }
	s_setprio 0
	s_add_i32 s30, s41, s9
	v_lshl_add_u64 v[210:211], v[210:211], 0, s[12:13]
	s_mov_b32 m0, s30
	ds_read_b128 v[178:181], v161 offset:49152
	ds_read_b128 v[182:185], v161 offset:50176
	ds_read_b128 v[186:189], v161 offset:51200
	ds_read_b128 v[190:193], v161 offset:52224
	ds_read_b128 v[194:197], v161 offset:53248
	ds_read_b128 v[198:201], v161 offset:54272
	ds_read_b128 v[202:205], v161 offset:55296
	ds_read_b128 v[206:209], v161 offset:56320
	global_load_lds_dwordx4 v[210:211], off
	s_add_i32 m0, s30, 0x2000
	s_add_u32 s28, s28, 0x80080
	v_lshl_add_u64 v[210:211], v[212:213], 0, s[12:13]
	s_addc_u32 s29, s29, 0
	s_add_i32 s30, s57, s9
	global_load_lds_dwordx4 v[210:211], off
	v_lshl_add_u64 v[210:211], s[28:29], 0, v[134:135]
	s_mov_b32 m0, s30
	s_nop 0
	global_load_lds_dwordx4 v[210:211], off
	v_lshl_add_u64 v[210:211], s[28:29], 0, v[130:131]
	s_add_i32 m0, s30, 0x2000
	s_nop 0
	global_load_lds_dwordx4 v[210:211], off
	v_lshl_add_u64 v[210:211], v[214:215], 0, s[12:13]
	s_mov_b32 m0, s53
	s_nop 0
	global_load_lds_dwordx4 v[210:211], off
	v_lshl_add_u64 v[210:211], v[216:217], 0, s[12:13]
	s_mov_b32 m0, s54
	s_nop 0
	global_load_lds_dwordx4 v[210:211], off
	s_waitcnt vmcnt(8)
	s_waitcnt lgkmcnt(0)
	s_setprio 1
	s_barrier
	v_mfma_f32_16x16x32_bf16 v[62:65], v[142:145], v[178:181], v[62:65]
	v_mfma_f32_16x16x32_bf16 v[62:65], v[146:149], v[182:185], v[62:65]
	v_mfma_f32_16x16x32_bf16 v[58:61], v[150:153], v[178:181], v[58:61]
	v_mfma_f32_16x16x32_bf16 v[58:61], v[154:157], v[182:185], v[58:61]
	v_mfma_f32_16x16x32_bf16 v[42:45], v[150:153], v[186:189], v[42:45]
	v_mfma_f32_16x16x32_bf16 v[42:45], v[154:157], v[190:193], v[42:45]
	v_mfma_f32_16x16x32_bf16 v[46:49], v[142:145], v[186:189], v[46:49]
	v_mfma_f32_16x16x32_bf16 v[46:49], v[146:149], v[190:193], v[46:49]
	v_mfma_f32_16x16x32_bf16 v[30:33], v[142:145], v[194:197], v[30:33]
	v_mfma_f32_16x16x32_bf16 v[30:33], v[146:149], v[198:201], v[30:33]
	v_mfma_f32_16x16x32_bf16 v[26:29], v[150:153], v[194:197], v[26:29]
	v_mfma_f32_16x16x32_bf16 v[26:29], v[154:157], v[198:201], v[26:29]
	v_mfma_f32_16x16x32_bf16 v[10:13], v[150:153], v[202:205], v[10:13]
	v_mfma_f32_16x16x32_bf16 v[10:13], v[154:157], v[206:209], v[10:13]
	v_mfma_f32_16x16x32_bf16 v[14:17], v[142:145], v[202:205], v[14:17]
	v_mfma_f32_16x16x32_bf16 v[14:17], v[146:149], v[206:209], v[14:17]
	v_mfma_f32_16x16x32_bf16 v[54:57], v[162:165], v[178:181], v[54:57]
	v_mfma_f32_16x16x32_bf16 v[54:57], v[166:169], v[182:185], v[54:57]
	v_mfma_f32_16x16x32_bf16 v[50:53], v[170:173], v[178:181], v[50:53]
	v_mfma_f32_16x16x32_bf16 v[50:53], v[174:177], v[182:185], v[50:53]
	v_mfma_f32_16x16x32_bf16 v[34:37], v[170:173], v[186:189], v[34:37]
	v_mfma_f32_16x16x32_bf16 v[34:37], v[174:177], v[190:193], v[34:37]
	v_mfma_f32_16x16x32_bf16 v[38:41], v[162:165], v[186:189], v[38:41]
	v_mfma_f32_16x16x32_bf16 v[38:41], v[166:169], v[190:193], v[38:41]
	v_mfma_f32_16x16x32_bf16 v[22:25], v[162:165], v[194:197], v[22:25]
	v_mfma_f32_16x16x32_bf16 v[22:25], v[166:169], v[198:201], v[22:25]
	v_mfma_f32_16x16x32_bf16 v[18:21], v[170:173], v[194:197], v[18:21]
	v_mfma_f32_16x16x32_bf16 v[18:21], v[174:177], v[198:201], v[18:21]
	v_mfma_f32_16x16x32_bf16 v[2:5], v[170:173], v[202:205], v[2:5]
	v_mfma_f32_16x16x32_bf16 v[2:5], v[174:177], v[206:209], v[2:5]
	v_mfma_f32_16x16x32_bf16 v[6:9], v[162:165], v[202:205], v[6:9]
	v_mfma_f32_16x16x32_bf16 v[6:9], v[166:169], v[206:209], v[6:9]
	s_barrier
	s_setprio 0
	s_add_i32 s40, s40, 2
	s_add_u32 s26, s26, 0x100
	s_addc_u32 s27, s27, 0
	s_add_u32 s21, s21, 0x100
	s_addc_u32 s35, s35, 0
	s_cmp_gt_u32 s40, 29
	s_cbranch_scc0 .LBB0_359
	s_and_b64 vcc, exec, s[16:17]
	s_cbranch_vccz .LBB0_362
	s_barrier

; #define PG8_STAGE(bufoff, gbase, voff) do { _Pragma("unroll") for (int _i = 0; _i < 2; ++_i) \
;         __builtin_amdgcn_global_load_lds((const unsigned*)((const char*)(gbase) + (voff)[_i]), (LAS unsigned*)(lds + (bufoff) + ldsw + _i * 8192), 16, 0, 0); } while (0)
; #define PG8_LDA(dst, b, h) do { _Pragma("unroll") for (int m = 0; m < 4; ++m) _Pragma("unroll") for (int k = 0; k < 2; ++k) dst[m][k] = *(const LAS bf16x8*)(lds + PG8_SA(b, h) + aoff + m * 2048 + k * 1024); } while (0)
; #define PG8_LDB(dst, b, h) do { _Pragma("unroll") for (int n = 0; n < 2; ++n) _Pragma("unroll") for (int k = 0; k < 2; ++k) dst[n][k] = *(const LAS bf16x8*)(lds + PG8_SB(b, h) + boff + n * 2048 + k * 1024); } while (0)
; #define PG8_MMA(ai, bj, At, Bt) do { __builtin_amdgcn_s_setprio(1); _Pragma("unroll") for (int m = 0; m < 4; ++m) _Pragma("unroll") for (int n = 0; n < 2; ++n) _Pragma("unroll") for (int k = 0; k < 2; ++k) \
;         acc[ai][bj][m][n] = __builtin_amdgcn_mfma_f32_16x16x32_bf16(Bt[n][k], At[m][k], acc[ai][bj][m][n], 0, 0, 0); __builtin_amdgcn_s_setprio(0); } while (0)
; #define PG8_WAIT_V(n) asm volatile("s_waitcnt vmcnt(" #n ")" ::: "memory")
; #define PG8_WAIT_L(n) asm volatile("s_waitcnt lgkmcnt(" #n ")" ::: "memory")
; template <class Epi, class Sched, bool ALIGN_EPI = false, bool SP2 = false>
; __device__ __forceinline__ void gemm_phase(LAS unsigned char* lds, const Gemm g, const Sched& S, const Epi& E) {
;     ...
;         for (int t = 0; t < nt; t += 2) {
;             const bool last = (t == nt - 2);
;             const char* a1 = cA + (size_t)(t + 1) * kstep;
;             const char* a2 = last ? nA : cA + (size_t)(t + 2) * kstep; const char* b2 = last ? nB : cB + (size_t)(t + 2) * kstep;
;             const char* a3 = a2 + kstep; const char* b3 = b2 + kstep;
;             if (last && has_next) S.a_ready(nxt);
;             if constexpr (SP2) {
;             PG8_LDB(B0, 0, 0); PG8_LDB(B1, 0, 1); PG8_SCHED; PG8_LDA(At, 0, 0); PG8_STAGE(PG8_SA(1, 1), a1 + hstep, voffA);
;             PG8_WAIT_V(8); PG8_WAIT_L(0); PG8_BAR; PG8_MMA(0, 0, At, B0); PG8_MMA(0, 1, At, B1); PG8_BAR; PG8_SCHED;
;             PG8_LDA(At, 0, 1); PG8_STAGE(PG8_SB(0, 0), b2, voffB); PG8_STAGE(PG8_SB(0, 1), b2 + hstep, voffB); PG8_STAGE(PG8_SA(0, 0), a2, voffA);
;             PG8_WAIT_V(8); PG8_WAIT_L(0); PG8_BAR; PG8_MMA(1, 0, At, B0); PG8_MMA(1, 1, At, B1); PG8_BAR; PG8_SCHED;
.LBB0_833:
	s_add_u32 s28, s26, 0xfff80080
	s_addc_u32 s29, s27, -1
	s_add_i32 s53, 0, 0x10000
	s_cmp_eq_u32 s52, 28
	s_cselect_b32 s31, s21, s29
	s_cselect_b32 s30, s48, s28
	s_cselect_b32 s29, s19, s51
	s_cselect_b32 s28, s49, s50
	s_add_i32 s56, 0, 0x14000
	v_add_u32_e32 v134, s53, v247
	v_add_u32_e32 v158, s56, v247
	ds_read_b128 v[106:109], v134
	ds_read_b128 v[110:113], v134 offset:1024
	ds_read_b128 v[122:125], v134 offset:2048
	ds_read_b128 v[134:137], v134 offset:3072
	ds_read_b128 v[146:149], v158
	ds_read_b128 v[150:153], v158 offset:1024
	ds_read_b128 v[154:157], v158 offset:2048
	ds_read_b128 v[158:161], v158 offset:3072
	v_lshl_add_u64 v[204:205], s[26:27], 0, v[200:201]
	s_add_i32 m0, s8, 0xc000
	ds_read_b128 v[162:165], v249
	ds_read_b128 v[166:169], v249 offset:1024
	ds_read_b128 v[170:173], v249 offset:2048
	ds_read_b128 v[174:177], v249 offset:3072
	ds_read_b128 v[178:181], v249 offset:4096
	ds_read_b128 v[182:185], v249 offset:5120
	ds_read_b128 v[186:189], v249 offset:6144
	ds_read_b128 v[190:193], v249 offset:7168
	global_load_lds_dwordx4 v[204:205], off
	v_lshl_add_u64 v[204:205], s[26:27], 0, v[202:203]
	s_add_i32 m0, s8, 0xe000
	s_nop 0
	global_load_lds_dwordx4 v[204:205], off
	s_waitcnt vmcnt(8)
	s_waitcnt lgkmcnt(0)
	s_setprio 1
	s_barrier
	v_mfma_f32_16x16x32_bf16 v[142:145], v[106:109], v[162:165], v[142:145]
	v_mfma_f32_16x16x32_bf16 v[142:145], v[110:113], v[166:169], v[142:145]
	v_mfma_f32_16x16x32_bf16 v[138:141], v[122:125], v[162:165], v[138:141]
	v_mfma_f32_16x16x32_bf16 v[138:141], v[134:137], v[166:169], v[138:141]
	v_mfma_f32_16x16x32_bf16 v[114:117], v[122:125], v[170:173], v[114:117]
	v_mfma_f32_16x16x32_bf16 v[114:117], v[134:137], v[174:177], v[114:117]
	v_mfma_f32_16x16x32_bf16 v[118:121], v[106:109], v[170:173], v[118:121]
	v_mfma_f32_16x16x32_bf16 v[118:121], v[110:113], v[174:177], v[118:121]
	v_mfma_f32_16x16x32_bf16 v[94:97], v[106:109], v[178:181], v[94:97]
	v_mfma_f32_16x16x32_bf16 v[94:97], v[110:113], v[182:185], v[94:97]
	v_mfma_f32_16x16x32_bf16 v[90:93], v[122:125], v[178:181], v[90:93]
	v_mfma_f32_16x16x32_bf16 v[90:93], v[134:137], v[182:185], v[90:93]
	v_mfma_f32_16x16x32_bf16 v[74:77], v[122:125], v[186:189], v[74:77]
	v_mfma_f32_16x16x32_bf16 v[74:77], v[134:137], v[190:193], v[74:77]
	v_mfma_f32_16x16x32_bf16 v[78:81], v[106:109], v[186:189], v[78:81]
	v_mfma_f32_16x16x32_bf16 v[78:81], v[110:113], v[190:193], v[78:81]
	v_mfma_f32_16x16x32_bf16 v[130:133], v[146:149], v[162:165], v[130:133]
	v_mfma_f32_16x16x32_bf16 v[130:133], v[150:153], v[166:169], v[130:133]
	v_mfma_f32_16x16x32_bf16 v[126:129], v[154:157], v[162:165], v[126:129]
	v_mfma_f32_16x16x32_bf16 v[126:129], v[158:161], v[166:169], v[126:129]
	v_mfma_f32_16x16x32_bf16 v[98:101], v[154:157], v[170:173], v[98:101]
	v_mfma_f32_16x16x32_bf16 v[98:101], v[158:161], v[174:177], v[98:101]
	v_mfma_f32_16x16x32_bf16 v[102:105], v[146:149], v[170:173], v[102:105]
	v_mfma_f32_16x16x32_bf16 v[102:105], v[150:153], v[174:177], v[102:105]
	v_mfma_f32_16x16x32_bf16 v[86:89], v[146:149], v[178:181], v[86:89]
	v_mfma_f32_16x16x32_bf16 v[86:89], v[150:153], v[182:185], v[86:89]
	v_mfma_f32_16x16x32_bf16 v[82:85], v[154:157], v[178:181], v[82:85]
	v_mfma_f32_16x16x32_bf16 v[82:85], v[158:161], v[182:185], v[82:85]
	v_mfma_f32_16x16x32_bf16 v[66:69], v[154:157], v[186:189], v[66:69]
	v_mfma_f32_16x16x32_bf16 v[66:69], v[158:161], v[190:193], v[66:69]
	v_mfma_f32_16x16x32_bf16 v[70:73], v[146:149], v[186:189], v[70:73]
	v_mfma_f32_16x16x32_bf16 v[70:73], v[150:153], v[190:193], v[70:73]
	s_barrier
	s_setprio 0
	s_add_i32 s53, s53, s7
	v_lshl_add_u64 v[204:205], s[28:29], 0, v[0:1]
	s_mov_b32 m0, s53
	ds_read_b128 v[162:165], v249 offset:16384
	ds_read_b128 v[166:169], v249 offset:17408
	ds_read_b128 v[170:173], v249 offset:18432
	ds_read_b128 v[174:177], v249 offset:19456
	ds_read_b128 v[178:181], v249 offset:20480
	ds_read_b128 v[182:185], v249 offset:21504
	ds_read_b128 v[186:189], v249 offset:22528
	ds_read_b128 v[190:193], v249 offset:23552
	global_load_lds_dwordx4 v[204:205], off
	s_add_i32 m0, s53, 0x2000
	s_add_u32 s54, s28, 0x80000
	v_lshl_add_u64 v[206:207], s[28:29], 0, v[194:195]
	s_addc_u32 s55, s29, 0
	s_add_i32 s53, s56, s7
	global_load_lds_dwordx4 v[206:207], off
	v_lshl_add_u64 v[208:209], s[54:55], 0, v[0:1]
	s_mov_b32 m0, s53
	v_lshl_add_u64 v[210:211], s[30:31], 0, v[196:197]
	global_load_lds_dwordx4 v[208:209], off
	v_lshl_add_u64 v[208:209], s[54:55], 0, v[194:195]
	s_add_i32 m0, s53, 0x2000
	s_nop 0
	global_load_lds_dwordx4 v[208:209], off
	v_lshl_add_u64 v[208:209], s[30:31], 0, v[198:199]
	s_mov_b32 m0, s8
	s_nop 0
	global_load_lds_dwordx4 v[208:209], off
	s_mov_b32 m0, s9
	s_nop 0
	global_load_lds_dwordx4 v[210:211], off
	s_waitcnt vmcnt(8)
	s_waitcnt lgkmcnt(0)
	s_setprio 1
	s_barrier
; #define PG8_STAGE(bufoff, gbase, voff) do { _Pragma("unroll") for (int _i = 0; _i < 2; ++_i) \
;         __builtin_amdgcn_global_load_lds((const unsigned*)((const char*)(gbase) + (voff)[_i]), (LAS unsigned*)(lds + (bufoff) + ldsw + _i * 8192), 16, 0, 0); } while (0)
; #define PG8_LDA(dst, b, h) do { _Pragma("unroll") for (int m = 0; m < 4; ++m) _Pragma("unroll") for (int k = 0; k < 2; ++k) dst[m][k] = *(const LAS bf16x8*)(lds + PG8_SA(b, h) + aoff + m * 2048 + k * 1024); } while (0)
; #define PG8_LDB(dst, b, h) do { _Pragma("unroll") for (int n = 0; n < 2; ++n) _Pragma("unroll") for (int k = 0; k < 2; ++k) dst[n][k] = *(const LAS bf16x8*)(lds + PG8_SB(b, h) + boff + n * 2048 + k * 1024); } while (0)
; #define PG8_MMA(ai, bj, At, Bt) do { __builtin_amdgcn_s_setprio(1); _Pragma("unroll") for (int m = 0; m < 4; ++m) _Pragma("unroll") for (int n = 0; n < 2; ++n) _Pragma("unroll") for (int k = 0; k < 2; ++k) \
;         acc[ai][bj][m][n] = __builtin_amdgcn_mfma_f32_16x16x32_bf16(Bt[n][k], At[m][k], acc[ai][bj][m][n], 0, 0, 0); __builtin_amdgcn_s_setprio(0); } while (0)
; #define PG8_WAIT_V(n) asm volatile("s_waitcnt vmcnt(" #n ")" ::: "memory")
; #define PG8_WAIT_L(n) asm volatile("s_waitcnt lgkmcnt(" #n ")" ::: "memory")
; #define PG8_BAR __builtin_amdgcn_s_barrier()
; #define PG8_SCHED __builtin_amdgcn_sched_barrier(0)
; template <class Epi, class Sched, bool ALIGN_EPI = false, bool SP2 = false>
; __device__ __forceinline__ void gemm_phase(LAS unsigned char* lds, const Gemm g, const Sched& S, const Epi& E) {
;     ...
;             PG8_WAIT_V(8); PG8_WAIT_L(0); PG8_BAR; PG8_MMA(1, 0, At, B0); PG8_MMA(1, 1, At, B1); PG8_BAR; PG8_SCHED;
;             PG8_LDB(B0, 1, 0); PG8_LDB(B1, 1, 1); PG8_SCHED; PG8_LDA(At, 1, 0); PG8_STAGE(PG8_SA(0, 1), a2 + hstep, voffA);
;             PG8_WAIT_V(8); PG8_WAIT_L(0); PG8_BAR; PG8_MMA(0, 0, At, B0); PG8_MMA(0, 1, At, B1); PG8_BAR; PG8_SCHED;
	v_mfma_f32_16x16x32_bf16 v[62:65], v[106:109], v[162:165], v[62:65]
	v_mfma_f32_16x16x32_bf16 v[62:65], v[110:113], v[166:169], v[62:65]
	v_mfma_f32_16x16x32_bf16 v[58:61], v[122:125], v[162:165], v[58:61]
	v_mfma_f32_16x16x32_bf16 v[58:61], v[134:137], v[166:169], v[58:61]
	v_mfma_f32_16x16x32_bf16 v[42:45], v[122:125], v[170:173], v[42:45]
	v_mfma_f32_16x16x32_bf16 v[42:45], v[134:137], v[174:177], v[42:45]
	v_mfma_f32_16x16x32_bf16 v[46:49], v[106:109], v[170:173], v[46:49]
	v_mfma_f32_16x16x32_bf16 v[46:49], v[110:113], v[174:177], v[46:49]
	v_mfma_f32_16x16x32_bf16 v[30:33], v[106:109], v[178:181], v[30:33]
	v_mfma_f32_16x16x32_bf16 v[30:33], v[110:113], v[182:185], v[30:33]
	v_mfma_f32_16x16x32_bf16 v[26:29], v[122:125], v[178:181], v[26:29]
	v_mfma_f32_16x16x32_bf16 v[26:29], v[134:137], v[182:185], v[26:29]
	v_mfma_f32_16x16x32_bf16 v[10:13], v[122:125], v[186:189], v[10:13]
	v_mfma_f32_16x16x32_bf16 v[10:13], v[134:137], v[190:193], v[10:13]
	v_mfma_f32_16x16x32_bf16 v[14:17], v[106:109], v[186:189], v[14:17]
	v_mfma_f32_16x16x32_bf16 v[14:17], v[110:113], v[190:193], v[14:17]
	v_mfma_f32_16x16x32_bf16 v[54:57], v[146:149], v[162:165], v[54:57]
	v_mfma_f32_16x16x32_bf16 v[54:57], v[150:153], v[166:169], v[54:57]
	v_mfma_f32_16x16x32_bf16 v[50:53], v[154:157], v[162:165], v[50:53]
	v_mfma_f32_16x16x32_bf16 v[50:53], v[158:161], v[166:169], v[50:53]
	v_mfma_f32_16x16x32_bf16 v[34:37], v[154:157], v[170:173], v[34:37]
	v_mfma_f32_16x16x32_bf16 v[34:37], v[158:161], v[174:177], v[34:37]
	v_mfma_f32_16x16x32_bf16 v[38:41], v[146:149], v[170:173], v[38:41]
	v_mfma_f32_16x16x32_bf16 v[38:41], v[150:153], v[174:177], v[38:41]
	v_mfma_f32_16x16x32_bf16 v[22:25], v[146:149], v[178:181], v[22:25]
	v_mfma_f32_16x16x32_bf16 v[22:25], v[150:153], v[182:185], v[22:25]
	v_mfma_f32_16x16x32_bf16 v[18:21], v[154:157], v[178:181], v[18:21]
	v_mfma_f32_16x16x32_bf16 v[18:21], v[158:161], v[182:185], v[18:21]
	v_mfma_f32_16x16x32_bf16 v[2:5], v[154:157], v[186:189], v[2:5]
	v_mfma_f32_16x16x32_bf16 v[2:5], v[158:161], v[190:193], v[2:5]
	v_mfma_f32_16x16x32_bf16 v[6:9], v[146:149], v[186:189], v[6:9]
	v_mfma_f32_16x16x32_bf16 v[6:9], v[150:153], v[190:193], v[6:9]
	s_barrier
	s_setprio 0
	s_add_i32 s53, 0, 0x18000
	s_add_i32 s54, 0, 0x1c000
	v_add_u32_e32 v134, s53, v247
	v_add_u32_e32 v158, s54, v247
	ds_read_b128 v[106:109], v134
	ds_read_b128 v[110:113], v134 offset:1024
	ds_read_b128 v[122:125], v134 offset:2048
	ds_read_b128 v[134:137], v134 offset:3072
	ds_read_b128 v[146:149], v158
	ds_read_b128 v[150:153], v158 offset:1024
	ds_read_b128 v[154:157], v158 offset:2048
	ds_read_b128 v[158:161], v158 offset:3072
	s_add_u32 s30, s30, 0x80000
	s_addc_u32 s31, s31, 0
	s_mov_b32 m0, s35
	v_lshl_add_u64 v[212:213], s[30:31], 0, v[198:199]
	ds_read_b128 v[162:165], v249 offset:32768
	ds_read_b128 v[166:169], v249 offset:33792
	ds_read_b128 v[170:173], v249 offset:34816
	ds_read_b128 v[174:177], v249 offset:35840
	ds_read_b128 v[178:181], v249 offset:36864
	ds_read_b128 v[182:185], v249 offset:37888
	ds_read_b128 v[186:189], v249 offset:38912
	ds_read_b128 v[190:193], v249 offset:39936
	global_load_lds_dwordx4 v[212:213], off
	v_lshl_add_u64 v[212:213], s[30:31], 0, v[196:197]
	s_mov_b32 m0, s42
	s_nop 0
	global_load_lds_dwordx4 v[212:213], off
	s_waitcnt vmcnt(8)
	s_waitcnt lgkmcnt(0)
	s_setprio 1
	s_barrier
	v_mfma_f32_16x16x32_bf16 v[142:145], v[106:109], v[162:165], v[142:145]
	v_mfma_f32_16x16x32_bf16 v[142:145], v[110:113], v[166:169], v[142:145]
	v_mfma_f32_16x16x32_bf16 v[138:141], v[122:125], v[162:165], v[138:141]
	v_mfma_f32_16x16x32_bf16 v[138:141], v[134:137], v[166:169], v[138:141]
	v_mfma_f32_16x16x32_bf16 v[114:117], v[122:125], v[170:173], v[114:117]
	v_mfma_f32_16x16x32_bf16 v[114:117], v[134:137], v[174:177], v[114:117]
	v_mfma_f32_16x16x32_bf16 v[118:121], v[106:109], v[170:173], v[118:121]
	v_mfma_f32_16x16x32_bf16 v[118:121], v[110:113], v[174:177], v[118:121]
	v_mfma_f32_16x16x32_bf16 v[94:97], v[106:109], v[178:181], v[94:97]
	v_mfma_f32_16x16x32_bf16 v[94:97], v[110:113], v[182:185], v[94:97]
	v_mfma_f32_16x16x32_bf16 v[90:93], v[122:125], v[178:181], v[90:93]
	v_mfma_f32_16x16x32_bf16 v[90:93], v[134:137], v[182:185], v[90:93]
	v_mfma_f32_16x16x32_bf16 v[74:77], v[122:125], v[186:189], v[74:77]
	v_mfma_f32_16x16x32_bf16 v[74:77], v[134:137], v[190:193], v[74:77]
	v_mfma_f32_16x16x32_bf16 v[78:81], v[106:109], v[186:189], v[78:81]
	v_mfma_f32_16x16x32_bf16 v[78:81], v[110:113], v[190:193], v[78:81]
	v_mfma_f32_16x16x32_bf16 v[130:133], v[146:149], v[162:165], v[130:133]
	v_mfma_f32_16x16x32_bf16 v[130:133], v[150:153], v[166:169], v[130:133]
	v_mfma_f32_16x16x32_bf16 v[126:129], v[154:157], v[162:165], v[126:129]
	v_mfma_f32_16x16x32_bf16 v[126:129], v[158:161], v[166:169], v[126:129]
	v_mfma_f32_16x16x32_bf16 v[98:101], v[154:157], v[170:173], v[98:101]
	v_mfma_f32_16x16x32_bf16 v[98:101], v[158:161], v[174:177], v[98:101]
	v_mfma_f32_16x16x32_bf16 v[102:105], v[146:149], v[170:173], v[102:105]
	v_mfma_f32_16x16x32_bf16 v[102:105], v[150:153], v[174:177], v[102:105]
	v_mfma_f32_16x16x32_bf16 v[86:89], v[146:149], v[178:181], v[86:89]
	v_mfma_f32_16x16x32_bf16 v[86:89], v[150:153], v[182:185], v[86:89]
	v_mfma_f32_16x16x32_bf16 v[82:85], v[154:157], v[178:181], v[82:85]
	v_mfma_f32_16x16x32_bf16 v[82:85], v[158:161], v[182:185], v[82:85]
	v_mfma_f32_16x16x32_bf16 v[66:69], v[154:157], v[186:189], v[66:69]
	v_mfma_f32_16x16x32_bf16 v[66:69], v[158:161], v[190:193], v[66:69]
	v_mfma_f32_16x16x32_bf16 v[70:73], v[146:149], v[186:189], v[70:73]
	v_mfma_f32_16x16x32_bf16 v[70:73], v[150:153], v[190:193], v[70:73]
	s_barrier
; #define PG8_STAGE(bufoff, gbase, voff) do { _Pragma("unroll") for (int _i = 0; _i < 2; ++_i) \
;         __builtin_amdgcn_global_load_lds((const unsigned*)((const char*)(gbase) + (voff)[_i]), (LAS unsigned*)(lds + (bufoff) + ldsw + _i * 8192), 16, 0, 0); } while (0)
; #define PG8_LDA(dst, b, h) do { _Pragma("unroll") for (int m = 0; m < 4; ++m) _Pragma("unroll") for (int k = 0; k < 2; ++k) dst[m][k] = *(const LAS bf16x8*)(lds + PG8_SA(b, h) + aoff + m * 2048 + k * 1024); } while (0)
; #define PG8_MMA(ai, bj, At, Bt) do { __builtin_amdgcn_s_setprio(1); _Pragma("unroll") for (int m = 0; m < 4; ++m) _Pragma("unroll") for (int n = 0; n < 2; ++n) _Pragma("unroll") for (int k = 0; k < 2; ++k) \
;         acc[ai][bj][m][n] = __builtin_amdgcn_mfma_f32_16x16x32_bf16(Bt[n][k], At[m][k], acc[ai][bj][m][n], 0, 0, 0); __builtin_amdgcn_s_setprio(0); } while (0)
; #define PG8_WAIT_V(n) asm volatile("s_waitcnt vmcnt(" #n ")" ::: "memory")
; #define PG8_WAIT_L(n) asm volatile("s_waitcnt lgkmcnt(" #n ")" ::: "memory")
; #define PG8_BAR __builtin_amdgcn_s_barrier()
; #define PG8_SCHED __builtin_amdgcn_sched_barrier(0)
; template <class Epi, class Sched, bool ALIGN_EPI = false, bool SP2 = false>
; __device__ __forceinline__ void gemm_phase(LAS unsigned char* lds, const Gemm g, const Sched& S, const Epi& E) {
;     ...
;         for (int t = 0; t < nt; t += 2) {
;             const bool last = (t == nt - 2);
;             const char* a1 = cA + (size_t)(t + 1) * kstep;
;             const char* a2 = last ? nA : cA + (size_t)(t + 2) * kstep; const char* b2 = last ? nB : cB + (size_t)(t + 2) * kstep;
;             const char* a3 = a2 + kstep; const char* b3 = b2 + kstep;
;             if (last && has_next) S.a_ready(nxt);
;     ...
;             PG8_WAIT_V(8); PG8_WAIT_L(0); PG8_BAR; PG8_MMA(0, 0, At, B0); PG8_MMA(0, 1, At, B1); PG8_BAR; PG8_SCHED;
;             PG8_LDA(At, 1, 1); PG8_STAGE(PG8_SB(1, 0), b3, voffB); PG8_STAGE(PG8_SB(1, 1), b3 + hstep, voffB); PG8_STAGE(PG8_SA(1, 0), a3, voffA);
;             PG8_WAIT_V(8); PG8_WAIT_L(0); PG8_BAR; PG8_MMA(1, 0, At, B0); PG8_MMA(1, 1, At, B1); PG8_BAR; PG8_SCHED;
	s_setprio 0
	s_add_i32 s30, s53, s7
	v_lshl_add_u64 v[204:205], v[204:205], 0, s[12:13]
	s_mov_b32 m0, s30
	ds_read_b128 v[162:165], v249 offset:49152
	ds_read_b128 v[166:169], v249 offset:50176
	ds_read_b128 v[170:173], v249 offset:51200
	ds_read_b128 v[174:177], v249 offset:52224
	ds_read_b128 v[178:181], v249 offset:53248
	ds_read_b128 v[182:185], v249 offset:54272
	ds_read_b128 v[186:189], v249 offset:55296
	ds_read_b128 v[190:193], v249 offset:56320
	global_load_lds_dwordx4 v[204:205], off
	s_add_i32 m0, s30, 0x2000
	s_add_u32 s28, s28, 0x80080
	v_lshl_add_u64 v[204:205], v[206:207], 0, s[12:13]
	s_addc_u32 s29, s29, 0
	s_add_i32 s30, s54, s7
	global_load_lds_dwordx4 v[204:205], off
	v_lshl_add_u64 v[204:205], s[28:29], 0, v[0:1]
	s_mov_b32 m0, s30
	s_nop 0
	global_load_lds_dwordx4 v[204:205], off
	v_lshl_add_u64 v[204:205], s[28:29], 0, v[194:195]
	s_add_i32 m0, s30, 0x2000
	s_nop 0
	global_load_lds_dwordx4 v[204:205], off
	v_lshl_add_u64 v[204:205], v[208:209], 0, s[12:13]
	s_mov_b32 m0, s43
	s_nop 0
	global_load_lds_dwordx4 v[204:205], off
	v_lshl_add_u64 v[204:205], v[210:211], 0, s[12:13]
	s_mov_b32 m0, s44
	s_nop 0
	global_load_lds_dwordx4 v[204:205], off
	s_waitcnt vmcnt(8)
	s_waitcnt lgkmcnt(0)
	s_setprio 1
	s_barrier
	v_mfma_f32_16x16x32_bf16 v[62:65], v[106:109], v[162:165], v[62:65]
	v_mfma_f32_16x16x32_bf16 v[62:65], v[110:113], v[166:169], v[62:65]
	v_mfma_f32_16x16x32_bf16 v[58:61], v[122:125], v[162:165], v[58:61]
	v_mfma_f32_16x16x32_bf16 v[58:61], v[134:137], v[166:169], v[58:61]
	v_mfma_f32_16x16x32_bf16 v[42:45], v[122:125], v[170:173], v[42:45]
	v_mfma_f32_16x16x32_bf16 v[42:45], v[134:137], v[174:177], v[42:45]
	v_mfma_f32_16x16x32_bf16 v[46:49], v[106:109], v[170:173], v[46:49]
	v_mfma_f32_16x16x32_bf16 v[46:49], v[110:113], v[174:177], v[46:49]
	v_mfma_f32_16x16x32_bf16 v[30:33], v[106:109], v[178:181], v[30:33]
	v_mfma_f32_16x16x32_bf16 v[30:33], v[110:113], v[182:185], v[30:33]
	v_mfma_f32_16x16x32_bf16 v[26:29], v[122:125], v[178:181], v[26:29]
	v_mfma_f32_16x16x32_bf16 v[26:29], v[134:137], v[182:185], v[26:29]
	v_mfma_f32_16x16x32_bf16 v[10:13], v[122:125], v[186:189], v[10:13]
	v_mfma_f32_16x16x32_bf16 v[10:13], v[134:137], v[190:193], v[10:13]
	v_mfma_f32_16x16x32_bf16 v[14:17], v[106:109], v[186:189], v[14:17]
	v_mfma_f32_16x16x32_bf16 v[14:17], v[110:113], v[190:193], v[14:17]
	v_mfma_f32_16x16x32_bf16 v[54:57], v[146:149], v[162:165], v[54:57]
	v_mfma_f32_16x16x32_bf16 v[54:57], v[150:153], v[166:169], v[54:57]
	v_mfma_f32_16x16x32_bf16 v[50:53], v[154:157], v[162:165], v[50:53]
	v_mfma_f32_16x16x32_bf16 v[50:53], v[158:161], v[166:169], v[50:53]
	v_mfma_f32_16x16x32_bf16 v[34:37], v[154:157], v[170:173], v[34:37]
	v_mfma_f32_16x16x32_bf16 v[34:37], v[158:161], v[174:177], v[34:37]
	v_mfma_f32_16x16x32_bf16 v[38:41], v[146:149], v[170:173], v[38:41]
	v_mfma_f32_16x16x32_bf16 v[38:41], v[150:153], v[174:177], v[38:41]
	v_mfma_f32_16x16x32_bf16 v[22:25], v[146:149], v[178:181], v[22:25]
	v_mfma_f32_16x16x32_bf16 v[22:25], v[150:153], v[182:185], v[22:25]
	v_mfma_f32_16x16x32_bf16 v[18:21], v[154:157], v[178:181], v[18:21]
	v_mfma_f32_16x16x32_bf16 v[18:21], v[158:161], v[182:185], v[18:21]
	v_mfma_f32_16x16x32_bf16 v[2:5], v[154:157], v[186:189], v[2:5]
	v_mfma_f32_16x16x32_bf16 v[2:5], v[158:161], v[190:193], v[2:5]
	v_mfma_f32_16x16x32_bf16 v[6:9], v[146:149], v[186:189], v[6:9]
	v_mfma_f32_16x16x32_bf16 v[6:9], v[150:153], v[190:193], v[6:9]
	s_barrier
	s_setprio 0
	s_add_i32 s52, s52, 2
	s_add_u32 s26, s26, 0x100
	s_addc_u32 s27, s27, 0
	s_add_u32 s50, s50, 0x100
	s_addc_u32 s51, s51, 0
	s_cmp_gt_u32 s52, 29
	s_cbranch_scc0 .LBB0_833
	s_and_b64 vcc, exec, s[16:17]
	s_cbranch_vccz .LBB0_836
	s_barrier

; #define PG8_STAGE(bufoff, gbase, voff) do { _Pragma("unroll") for (int _i = 0; _i < 2; ++_i) \
;         __builtin_amdgcn_global_load_lds((const unsigned*)((const char*)(gbase) + (voff)[_i]), (LAS unsigned*)(lds + (bufoff) + ldsw + _i * 8192), 16, 0, 0); } while (0)
; #define PG8_LDA(dst, b, h) do { _Pragma("unroll") for (int m = 0; m < 4; ++m) _Pragma("unroll") for (int k = 0; k < 2; ++k) dst[m][k] = *(const LAS bf16x8*)(lds + PG8_SA(b, h) + aoff + m * 2048 + k * 1024); } while (0)
; #define PG8_LDB(dst, b, h) do { _Pragma("unroll") for (int n = 0; n < 2; ++n) _Pragma("unroll") for (int k = 0; k < 2; ++k) dst[n][k] = *(const LAS bf16x8*)(lds + PG8_SB(b, h) + boff + n * 2048 + k * 1024); } while (0)
; #define PG8_MMA(ai, bj, At, Bt) do { __builtin_amdgcn_s_setprio(1); _Pragma("unroll") for (int m = 0; m < 4; ++m) _Pragma("unroll") for (int n = 0; n < 2; ++n) _Pragma("unroll") for (int k = 0; k < 2; ++k) \
;         acc[ai][bj][m][n] = __builtin_amdgcn_mfma_f32_16x16x32_bf16(Bt[n][k], At[m][k], acc[ai][bj][m][n], 0, 0, 0); __builtin_amdgcn_s_setprio(0); } while (0)
; #define PG8_WAIT_V(n) asm volatile("s_waitcnt vmcnt(" #n ")" ::: "memory")
; #define PG8_WAIT_L(n) asm volatile("s_waitcnt lgkmcnt(" #n ")" ::: "memory")
; template <class Epi, class Sched, bool ALIGN_EPI = false, bool SP2 = false>
; __device__ __forceinline__ void gemm_phase(LAS unsigned char* lds, const Gemm g, const Sched& S, const Epi& E) {
;     ...
;         for (int t = 0; t < nt; t += 2) {
;             const bool last = (t == nt - 2);
;             const char* a1 = cA + (size_t)(t + 1) * kstep;
;             const char* a2 = last ? nA : cA + (size_t)(t + 2) * kstep; const char* b2 = last ? nB : cB + (size_t)(t + 2) * kstep;
;             const char* a3 = a2 + kstep; const char* b3 = b2 + kstep;
;             if (last && has_next) S.a_ready(nxt);
;             if constexpr (SP2) {
;             PG8_LDB(B0, 0, 0); PG8_LDB(B1, 0, 1); PG8_SCHED; PG8_LDA(At, 0, 0); PG8_STAGE(PG8_SA(1, 1), a1 + hstep, voffA);
;             PG8_WAIT_V(8); PG8_WAIT_L(0); PG8_BAR; PG8_MMA(0, 0, At, B0); PG8_MMA(0, 1, At, B1); PG8_BAR; PG8_SCHED;
;             PG8_LDA(At, 0, 1); PG8_STAGE(PG8_SB(0, 0), b2, voffB); PG8_STAGE(PG8_SB(0, 1), b2 + hstep, voffB); PG8_STAGE(PG8_SA(0, 0), a2, voffA);
;             PG8_WAIT_V(8); PG8_WAIT_L(0); PG8_BAR; PG8_MMA(1, 0, At, B0); PG8_MMA(1, 1, At, B1); PG8_BAR; PG8_SCHED;
.LBB0_924:
	s_add_u32 s28, s26, 0xfff80080
	s_addc_u32 s29, s27, -1
	s_add_i32 s51, 0, 0x10000
	s_cmp_eq_u32 s50, 28
	s_cselect_b32 s31, s7, s29
	s_cselect_b32 s30, s8, s28
	v_add_u32_e32 v148, s51, v151
	s_cselect_b32 s29, s19, s49
	s_cselect_b32 s28, s21, s35
	s_add_i32 s54, 0, 0x14000
	ds_read_b128 v[140:143], v148
	ds_read_b128 v[144:147], v148 offset:1024
	ds_read_b128 v[156:159], v148 offset:2048
	ds_read_b128 v[160:163], v148 offset:3072
	v_add_u32_e32 v148, s54, v151
	ds_read_b128 v[164:167], v148
	ds_read_b128 v[168:171], v148 offset:1024
	ds_read_b128 v[172:175], v148 offset:2048
	ds_read_b128 v[176:179], v148 offset:3072
	v_lshl_add_u64 v[212:213], s[26:27], 0, v[136:137]
	s_add_i32 m0, s42, 0xc000
	ds_read_b128 v[180:183], v155
	ds_read_b128 v[184:187], v155 offset:1024
	ds_read_b128 v[188:191], v155 offset:2048
	ds_read_b128 v[192:195], v155 offset:3072
	ds_read_b128 v[196:199], v155 offset:4096
	ds_read_b128 v[200:203], v155 offset:5120
	ds_read_b128 v[204:207], v155 offset:6144
	ds_read_b128 v[208:211], v155 offset:7168
	global_load_lds_dwordx4 v[212:213], off
	v_lshl_add_u64 v[212:213], s[26:27], 0, v[138:139]
	s_add_i32 m0, s42, 0xe000
	s_nop 0
	global_load_lds_dwordx4 v[212:213], off
	s_waitcnt vmcnt(8)
	s_waitcnt lgkmcnt(0)
	s_setprio 1
	s_barrier
	v_mfma_f32_16x16x32_bf16 v[126:129], v[140:143], v[180:183], v[126:129]
	v_mfma_f32_16x16x32_bf16 v[126:129], v[144:147], v[184:187], v[126:129]
	v_mfma_f32_16x16x32_bf16 v[122:125], v[156:159], v[180:183], v[122:125]
	v_mfma_f32_16x16x32_bf16 v[122:125], v[160:163], v[184:187], v[122:125]
	v_mfma_f32_16x16x32_bf16 v[106:109], v[156:159], v[188:191], v[106:109]
	v_mfma_f32_16x16x32_bf16 v[106:109], v[160:163], v[192:195], v[106:109]
	v_mfma_f32_16x16x32_bf16 v[110:113], v[140:143], v[188:191], v[110:113]
	v_mfma_f32_16x16x32_bf16 v[110:113], v[144:147], v[192:195], v[110:113]
	v_mfma_f32_16x16x32_bf16 v[94:97], v[140:143], v[196:199], v[94:97]
	v_mfma_f32_16x16x32_bf16 v[94:97], v[144:147], v[200:203], v[94:97]
	v_mfma_f32_16x16x32_bf16 v[90:93], v[156:159], v[196:199], v[90:93]
	v_mfma_f32_16x16x32_bf16 v[90:93], v[160:163], v[200:203], v[90:93]
	v_mfma_f32_16x16x32_bf16 v[74:77], v[156:159], v[204:207], v[74:77]
	v_mfma_f32_16x16x32_bf16 v[74:77], v[160:163], v[208:211], v[74:77]
	v_mfma_f32_16x16x32_bf16 v[78:81], v[140:143], v[204:207], v[78:81]
	v_mfma_f32_16x16x32_bf16 v[78:81], v[144:147], v[208:211], v[78:81]
	v_mfma_f32_16x16x32_bf16 v[118:121], v[164:167], v[180:183], v[118:121]
	v_mfma_f32_16x16x32_bf16 v[118:121], v[168:171], v[184:187], v[118:121]
	v_mfma_f32_16x16x32_bf16 v[114:117], v[172:175], v[180:183], v[114:117]
	v_mfma_f32_16x16x32_bf16 v[114:117], v[176:179], v[184:187], v[114:117]
	v_mfma_f32_16x16x32_bf16 v[98:101], v[172:175], v[188:191], v[98:101]
	v_mfma_f32_16x16x32_bf16 v[98:101], v[176:179], v[192:195], v[98:101]
	v_mfma_f32_16x16x32_bf16 v[102:105], v[164:167], v[188:191], v[102:105]
	v_mfma_f32_16x16x32_bf16 v[102:105], v[168:171], v[192:195], v[102:105]
	v_mfma_f32_16x16x32_bf16 v[86:89], v[164:167], v[196:199], v[86:89]
	v_mfma_f32_16x16x32_bf16 v[86:89], v[168:171], v[200:203], v[86:89]
	v_mfma_f32_16x16x32_bf16 v[82:85], v[172:175], v[196:199], v[82:85]
	v_mfma_f32_16x16x32_bf16 v[82:85], v[176:179], v[200:203], v[82:85]
	v_mfma_f32_16x16x32_bf16 v[66:69], v[172:175], v[204:207], v[66:69]
	v_mfma_f32_16x16x32_bf16 v[66:69], v[176:179], v[208:211], v[66:69]
	v_mfma_f32_16x16x32_bf16 v[70:73], v[164:167], v[204:207], v[70:73]
	v_mfma_f32_16x16x32_bf16 v[70:73], v[168:171], v[208:211], v[70:73]
	s_barrier
	s_setprio 0
	s_add_i32 s51, s51, s41
	v_lshl_add_u64 v[212:213], s[28:29], 0, v[0:1]
	s_mov_b32 m0, s51
	ds_read_b128 v[180:183], v155 offset:16384
	ds_read_b128 v[184:187], v155 offset:17408
	ds_read_b128 v[188:191], v155 offset:18432
	ds_read_b128 v[192:195], v155 offset:19456
	ds_read_b128 v[196:199], v155 offset:20480
	ds_read_b128 v[200:203], v155 offset:21504
	ds_read_b128 v[204:207], v155 offset:22528
	ds_read_b128 v[208:211], v155 offset:23552
	global_load_lds_dwordx4 v[212:213], off
	s_add_i32 m0, s51, 0x2000
	s_add_u32 s52, s28, 0x80000
	v_lshl_add_u64 v[214:215], s[28:29], 0, v[130:131]
	s_addc_u32 s53, s29, 0
	s_add_i32 s51, s54, s41
	global_load_lds_dwordx4 v[214:215], off
	v_lshl_add_u64 v[216:217], s[52:53], 0, v[0:1]
	s_mov_b32 m0, s51
	v_lshl_add_u64 v[218:219], s[30:31], 0, v[132:133]
	global_load_lds_dwordx4 v[216:217], off
	v_lshl_add_u64 v[216:217], s[52:53], 0, v[130:131]
	s_add_i32 m0, s51, 0x2000
	s_nop 0
	global_load_lds_dwordx4 v[216:217], off
	v_lshl_add_u64 v[216:217], s[30:31], 0, v[134:135]
	s_mov_b32 m0, s42
	s_nop 0
	global_load_lds_dwordx4 v[216:217], off
	s_mov_b32 m0, s43
	s_nop 0
	global_load_lds_dwordx4 v[218:219], off
	s_waitcnt vmcnt(8)
	s_waitcnt lgkmcnt(0)
	s_setprio 1
	s_barrier
; #define PG8_STAGE(bufoff, gbase, voff) do { _Pragma("unroll") for (int _i = 0; _i < 2; ++_i) \
;         __builtin_amdgcn_global_load_lds((const unsigned*)((const char*)(gbase) + (voff)[_i]), (LAS unsigned*)(lds + (bufoff) + ldsw + _i * 8192), 16, 0, 0); } while (0)
; #define PG8_LDA(dst, b, h) do { _Pragma("unroll") for (int m = 0; m < 4; ++m) _Pragma("unroll") for (int k = 0; k < 2; ++k) dst[m][k] = *(const LAS bf16x8*)(lds + PG8_SA(b, h) + aoff + m * 2048 + k * 1024); } while (0)
; #define PG8_LDB(dst, b, h) do { _Pragma("unroll") for (int n = 0; n < 2; ++n) _Pragma("unroll") for (int k = 0; k < 2; ++k) dst[n][k] = *(const LAS bf16x8*)(lds + PG8_SB(b, h) + boff + n * 2048 + k * 1024); } while (0)
; #define PG8_MMA(ai, bj, At, Bt) do { __builtin_amdgcn_s_setprio(1); _Pragma("unroll") for (int m = 0; m < 4; ++m) _Pragma("unroll") for (int n = 0; n < 2; ++n) _Pragma("unroll") for (int k = 0; k < 2; ++k) \
;         acc[ai][bj][m][n] = __builtin_amdgcn_mfma_f32_16x16x32_bf16(Bt[n][k], At[m][k], acc[ai][bj][m][n], 0, 0, 0); __builtin_amdgcn_s_setprio(0); } while (0)
; #define PG8_WAIT_V(n) asm volatile("s_waitcnt vmcnt(" #n ")" ::: "memory")
; #define PG8_WAIT_L(n) asm volatile("s_waitcnt lgkmcnt(" #n ")" ::: "memory")
; #define PG8_BAR __builtin_amdgcn_s_barrier()
; #define PG8_SCHED __builtin_amdgcn_sched_barrier(0)
; template <class Epi, class Sched, bool ALIGN_EPI = false, bool SP2 = false>
; __device__ __forceinline__ void gemm_phase(LAS unsigned char* lds, const Gemm g, const Sched& S, const Epi& E) {
;     ...
;             PG8_WAIT_V(8); PG8_WAIT_L(0); PG8_BAR; PG8_MMA(1, 0, At, B0); PG8_MMA(1, 1, At, B1); PG8_BAR; PG8_SCHED;
;             PG8_LDB(B0, 1, 0); PG8_LDB(B1, 1, 1); PG8_SCHED; PG8_LDA(At, 1, 0); PG8_STAGE(PG8_SA(0, 1), a2 + hstep, voffA);
;             PG8_WAIT_V(8); PG8_WAIT_L(0); PG8_BAR; PG8_MMA(0, 0, At, B0); PG8_MMA(0, 1, At, B1); PG8_BAR; PG8_SCHED;
	v_mfma_f32_16x16x32_bf16 v[62:65], v[140:143], v[180:183], v[62:65]
	v_mfma_f32_16x16x32_bf16 v[62:65], v[144:147], v[184:187], v[62:65]
	v_mfma_f32_16x16x32_bf16 v[58:61], v[156:159], v[180:183], v[58:61]
	v_mfma_f32_16x16x32_bf16 v[58:61], v[160:163], v[184:187], v[58:61]
	v_mfma_f32_16x16x32_bf16 v[42:45], v[156:159], v[188:191], v[42:45]
	v_mfma_f32_16x16x32_bf16 v[42:45], v[160:163], v[192:195], v[42:45]
	v_mfma_f32_16x16x32_bf16 v[46:49], v[140:143], v[188:191], v[46:49]
	v_mfma_f32_16x16x32_bf16 v[46:49], v[144:147], v[192:195], v[46:49]
	v_mfma_f32_16x16x32_bf16 v[30:33], v[140:143], v[196:199], v[30:33]
	v_mfma_f32_16x16x32_bf16 v[30:33], v[144:147], v[200:203], v[30:33]
	v_mfma_f32_16x16x32_bf16 v[26:29], v[156:159], v[196:199], v[26:29]
	v_mfma_f32_16x16x32_bf16 v[26:29], v[160:163], v[200:203], v[26:29]
	v_mfma_f32_16x16x32_bf16 v[10:13], v[156:159], v[204:207], v[10:13]
	v_mfma_f32_16x16x32_bf16 v[10:13], v[160:163], v[208:211], v[10:13]
	v_mfma_f32_16x16x32_bf16 v[14:17], v[140:143], v[204:207], v[14:17]
	v_mfma_f32_16x16x32_bf16 v[14:17], v[144:147], v[208:211], v[14:17]
	v_mfma_f32_16x16x32_bf16 v[54:57], v[164:167], v[180:183], v[54:57]
	v_mfma_f32_16x16x32_bf16 v[54:57], v[168:171], v[184:187], v[54:57]
	v_mfma_f32_16x16x32_bf16 v[50:53], v[172:175], v[180:183], v[50:53]
	v_mfma_f32_16x16x32_bf16 v[50:53], v[176:179], v[184:187], v[50:53]
	v_mfma_f32_16x16x32_bf16 v[34:37], v[172:175], v[188:191], v[34:37]
	v_mfma_f32_16x16x32_bf16 v[34:37], v[176:179], v[192:195], v[34:37]
	v_mfma_f32_16x16x32_bf16 v[38:41], v[164:167], v[188:191], v[38:41]
	v_mfma_f32_16x16x32_bf16 v[38:41], v[168:171], v[192:195], v[38:41]
	v_mfma_f32_16x16x32_bf16 v[22:25], v[164:167], v[196:199], v[22:25]
	v_mfma_f32_16x16x32_bf16 v[22:25], v[168:171], v[200:203], v[22:25]
	v_mfma_f32_16x16x32_bf16 v[18:21], v[172:175], v[196:199], v[18:21]
	v_mfma_f32_16x16x32_bf16 v[18:21], v[176:179], v[200:203], v[18:21]
	v_mfma_f32_16x16x32_bf16 v[2:5], v[172:175], v[204:207], v[2:5]
	v_mfma_f32_16x16x32_bf16 v[2:5], v[176:179], v[208:211], v[2:5]
	v_mfma_f32_16x16x32_bf16 v[6:9], v[164:167], v[204:207], v[6:9]
	v_mfma_f32_16x16x32_bf16 v[6:9], v[168:171], v[208:211], v[6:9]
	s_barrier
	s_setprio 0
	s_add_i32 s51, 0, 0x18000
	v_add_u32_e32 v148, s51, v151
	s_add_i32 s52, 0, 0x1c000
	ds_read_b128 v[140:143], v148
	ds_read_b128 v[144:147], v148 offset:1024
	ds_read_b128 v[156:159], v148 offset:2048
	ds_read_b128 v[160:163], v148 offset:3072
	v_add_u32_e32 v148, s52, v151
	ds_read_b128 v[164:167], v148
	ds_read_b128 v[168:171], v148 offset:1024
	ds_read_b128 v[172:175], v148 offset:2048
	ds_read_b128 v[176:179], v148 offset:3072
	s_add_u32 s30, s30, 0x80000
	s_addc_u32 s31, s31, 0
	s_mov_b32 m0, s44
	v_lshl_add_u64 v[220:221], s[30:31], 0, v[134:135]
	ds_read_b128 v[180:183], v155 offset:32768
	ds_read_b128 v[184:187], v155 offset:33792
	ds_read_b128 v[188:191], v155 offset:34816
	ds_read_b128 v[192:195], v155 offset:35840
	ds_read_b128 v[196:199], v155 offset:36864
	ds_read_b128 v[200:203], v155 offset:37888
	ds_read_b128 v[204:207], v155 offset:38912
	ds_read_b128 v[208:211], v155 offset:39936
	global_load_lds_dwordx4 v[220:221], off
	v_lshl_add_u64 v[220:221], s[30:31], 0, v[132:133]
	s_mov_b32 m0, s45
	s_nop 0
	global_load_lds_dwordx4 v[220:221], off
	s_waitcnt vmcnt(8)
	s_waitcnt lgkmcnt(0)
	s_setprio 1
	s_barrier
	v_mfma_f32_16x16x32_bf16 v[126:129], v[140:143], v[180:183], v[126:129]
	v_mfma_f32_16x16x32_bf16 v[126:129], v[144:147], v[184:187], v[126:129]
	v_mfma_f32_16x16x32_bf16 v[122:125], v[156:159], v[180:183], v[122:125]
	v_mfma_f32_16x16x32_bf16 v[122:125], v[160:163], v[184:187], v[122:125]
	v_mfma_f32_16x16x32_bf16 v[106:109], v[156:159], v[188:191], v[106:109]
	v_mfma_f32_16x16x32_bf16 v[106:109], v[160:163], v[192:195], v[106:109]
	v_mfma_f32_16x16x32_bf16 v[110:113], v[140:143], v[188:191], v[110:113]
	v_mfma_f32_16x16x32_bf16 v[110:113], v[144:147], v[192:195], v[110:113]
	v_mfma_f32_16x16x32_bf16 v[94:97], v[140:143], v[196:199], v[94:97]
	v_mfma_f32_16x16x32_bf16 v[94:97], v[144:147], v[200:203], v[94:97]
	v_mfma_f32_16x16x32_bf16 v[90:93], v[156:159], v[196:199], v[90:93]
	v_mfma_f32_16x16x32_bf16 v[90:93], v[160:163], v[200:203], v[90:93]
	v_mfma_f32_16x16x32_bf16 v[74:77], v[156:159], v[204:207], v[74:77]
	v_mfma_f32_16x16x32_bf16 v[74:77], v[160:163], v[208:211], v[74:77]
	v_mfma_f32_16x16x32_bf16 v[78:81], v[140:143], v[204:207], v[78:81]
	v_mfma_f32_16x16x32_bf16 v[78:81], v[144:147], v[208:211], v[78:81]
	v_mfma_f32_16x16x32_bf16 v[118:121], v[164:167], v[180:183], v[118:121]
	v_mfma_f32_16x16x32_bf16 v[118:121], v[168:171], v[184:187], v[118:121]
	v_mfma_f32_16x16x32_bf16 v[114:117], v[172:175], v[180:183], v[114:117]
	v_mfma_f32_16x16x32_bf16 v[114:117], v[176:179], v[184:187], v[114:117]
	v_mfma_f32_16x16x32_bf16 v[98:101], v[172:175], v[188:191], v[98:101]
	v_mfma_f32_16x16x32_bf16 v[98:101], v[176:179], v[192:195], v[98:101]
	v_mfma_f32_16x16x32_bf16 v[102:105], v[164:167], v[188:191], v[102:105]
	v_mfma_f32_16x16x32_bf16 v[102:105], v[168:171], v[192:195], v[102:105]
	v_mfma_f32_16x16x32_bf16 v[86:89], v[164:167], v[196:199], v[86:89]
	v_mfma_f32_16x16x32_bf16 v[86:89], v[168:171], v[200:203], v[86:89]
	v_mfma_f32_16x16x32_bf16 v[82:85], v[172:175], v[196:199], v[82:85]
	v_mfma_f32_16x16x32_bf16 v[82:85], v[176:179], v[200:203], v[82:85]
	v_mfma_f32_16x16x32_bf16 v[66:69], v[172:175], v[204:207], v[66:69]
	v_mfma_f32_16x16x32_bf16 v[66:69], v[176:179], v[208:211], v[66:69]
	v_mfma_f32_16x16x32_bf16 v[70:73], v[164:167], v[204:207], v[70:73]
	v_mfma_f32_16x16x32_bf16 v[70:73], v[168:171], v[208:211], v[70:73]
	s_barrier
; #define PG8_STAGE(bufoff, gbase, voff) do { _Pragma("unroll") for (int _i = 0; _i < 2; ++_i) \
;         __builtin_amdgcn_global_load_lds((const unsigned*)((const char*)(gbase) + (voff)[_i]), (LAS unsigned*)(lds + (bufoff) + ldsw + _i * 8192), 16, 0, 0); } while (0)
; #define PG8_LDA(dst, b, h) do { _Pragma("unroll") for (int m = 0; m < 4; ++m) _Pragma("unroll") for (int k = 0; k < 2; ++k) dst[m][k] = *(const LAS bf16x8*)(lds + PG8_SA(b, h) + aoff + m * 2048 + k * 1024); } while (0)
; #define PG8_MMA(ai, bj, At, Bt) do { __builtin_amdgcn_s_setprio(1); _Pragma("unroll") for (int m = 0; m < 4; ++m) _Pragma("unroll") for (int n = 0; n < 2; ++n) _Pragma("unroll") for (int k = 0; k < 2; ++k) \
;         acc[ai][bj][m][n] = __builtin_amdgcn_mfma_f32_16x16x32_bf16(Bt[n][k], At[m][k], acc[ai][bj][m][n], 0, 0, 0); __builtin_amdgcn_s_setprio(0); } while (0)
; #define PG8_WAIT_V(n) asm volatile("s_waitcnt vmcnt(" #n ")" ::: "memory")
; #define PG8_WAIT_L(n) asm volatile("s_waitcnt lgkmcnt(" #n ")" ::: "memory")
; #define PG8_BAR __builtin_amdgcn_s_barrier()
; #define PG8_SCHED __builtin_amdgcn_sched_barrier(0)
; template <class Epi, class Sched, bool ALIGN_EPI = false, bool SP2 = false>
; __device__ __forceinline__ void gemm_phase(LAS unsigned char* lds, const Gemm g, const Sched& S, const Epi& E) {
;     ...
;         for (int t = 0; t < nt; t += 2) {
;             const bool last = (t == nt - 2);
;             const char* a1 = cA + (size_t)(t + 1) * kstep;
;             const char* a2 = last ? nA : cA + (size_t)(t + 2) * kstep; const char* b2 = last ? nB : cB + (size_t)(t + 2) * kstep;
;             const char* a3 = a2 + kstep; const char* b3 = b2 + kstep;
;             if (last && has_next) S.a_ready(nxt);
;     ...
;             PG8_WAIT_V(8); PG8_WAIT_L(0); PG8_BAR; PG8_MMA(0, 0, At, B0); PG8_MMA(0, 1, At, B1); PG8_BAR; PG8_SCHED;
;             PG8_LDA(At, 1, 1); PG8_STAGE(PG8_SB(1, 0), b3, voffB); PG8_STAGE(PG8_SB(1, 1), b3 + hstep, voffB); PG8_STAGE(PG8_SA(1, 0), a3, voffA);
;             PG8_WAIT_V(8); PG8_WAIT_L(0); PG8_BAR; PG8_MMA(1, 0, At, B0); PG8_MMA(1, 1, At, B1); PG8_BAR; PG8_SCHED;
	s_setprio 0
	s_add_i32 s30, s51, s41
	v_lshl_add_u64 v[212:213], v[212:213], 0, s[12:13]
	s_mov_b32 m0, s30
	ds_read_b128 v[180:183], v155 offset:49152
	ds_read_b128 v[184:187], v155 offset:50176
	ds_read_b128 v[188:191], v155 offset:51200
	ds_read_b128 v[192:195], v155 offset:52224
	ds_read_b128 v[196:199], v155 offset:53248
	ds_read_b128 v[200:203], v155 offset:54272
	ds_read_b128 v[204:207], v155 offset:55296
	ds_read_b128 v[208:211], v155 offset:56320
	global_load_lds_dwordx4 v[212:213], off
	s_add_i32 m0, s30, 0x2000
	s_add_u32 s28, s28, 0x80080
	v_lshl_add_u64 v[212:213], v[214:215], 0, s[12:13]
	s_addc_u32 s29, s29, 0
	s_add_i32 s30, s52, s41
	global_load_lds_dwordx4 v[212:213], off
	v_lshl_add_u64 v[212:213], s[28:29], 0, v[0:1]
	s_mov_b32 m0, s30
	s_nop 0
	global_load_lds_dwordx4 v[212:213], off
	v_lshl_add_u64 v[212:213], s[28:29], 0, v[130:131]
	s_add_i32 m0, s30, 0x2000
	s_nop 0
	global_load_lds_dwordx4 v[212:213], off
	v_lshl_add_u64 v[212:213], v[216:217], 0, s[12:13]
	s_mov_b32 m0, s46
	s_nop 0
	global_load_lds_dwordx4 v[212:213], off
	v_lshl_add_u64 v[212:213], v[218:219], 0, s[12:13]
	s_mov_b32 m0, s47
	s_nop 0
	global_load_lds_dwordx4 v[212:213], off
	s_waitcnt vmcnt(8)
	s_waitcnt lgkmcnt(0)
	s_setprio 1
	s_barrier
	v_mfma_f32_16x16x32_bf16 v[62:65], v[140:143], v[180:183], v[62:65]
	v_mfma_f32_16x16x32_bf16 v[62:65], v[144:147], v[184:187], v[62:65]
	v_mfma_f32_16x16x32_bf16 v[58:61], v[156:159], v[180:183], v[58:61]
	v_mfma_f32_16x16x32_bf16 v[58:61], v[160:163], v[184:187], v[58:61]
	v_mfma_f32_16x16x32_bf16 v[42:45], v[156:159], v[188:191], v[42:45]
	v_mfma_f32_16x16x32_bf16 v[42:45], v[160:163], v[192:195], v[42:45]
	v_mfma_f32_16x16x32_bf16 v[46:49], v[140:143], v[188:191], v[46:49]
	v_mfma_f32_16x16x32_bf16 v[46:49], v[144:147], v[192:195], v[46:49]
	v_mfma_f32_16x16x32_bf16 v[30:33], v[140:143], v[196:199], v[30:33]
	v_mfma_f32_16x16x32_bf16 v[30:33], v[144:147], v[200:203], v[30:33]
	v_mfma_f32_16x16x32_bf16 v[26:29], v[156:159], v[196:199], v[26:29]
	v_mfma_f32_16x16x32_bf16 v[26:29], v[160:163], v[200:203], v[26:29]
	v_mfma_f32_16x16x32_bf16 v[10:13], v[156:159], v[204:207], v[10:13]
	v_mfma_f32_16x16x32_bf16 v[10:13], v[160:163], v[208:211], v[10:13]
	v_mfma_f32_16x16x32_bf16 v[14:17], v[140:143], v[204:207], v[14:17]
	v_mfma_f32_16x16x32_bf16 v[14:17], v[144:147], v[208:211], v[14:17]
	v_mfma_f32_16x16x32_bf16 v[54:57], v[164:167], v[180:183], v[54:57]
	v_mfma_f32_16x16x32_bf16 v[54:57], v[168:171], v[184:187], v[54:57]
	v_mfma_f32_16x16x32_bf16 v[50:53], v[172:175], v[180:183], v[50:53]
	v_mfma_f32_16x16x32_bf16 v[50:53], v[176:179], v[184:187], v[50:53]
	v_mfma_f32_16x16x32_bf16 v[34:37], v[172:175], v[188:191], v[34:37]
	v_mfma_f32_16x16x32_bf16 v[34:37], v[176:179], v[192:195], v[34:37]
	v_mfma_f32_16x16x32_bf16 v[38:41], v[164:167], v[188:191], v[38:41]
	v_mfma_f32_16x16x32_bf16 v[38:41], v[168:171], v[192:195], v[38:41]
	v_mfma_f32_16x16x32_bf16 v[22:25], v[164:167], v[196:199], v[22:25]
	v_mfma_f32_16x16x32_bf16 v[22:25], v[168:171], v[200:203], v[22:25]
	v_mfma_f32_16x16x32_bf16 v[18:21], v[172:175], v[196:199], v[18:21]
	v_mfma_f32_16x16x32_bf16 v[18:21], v[176:179], v[200:203], v[18:21]
	v_mfma_f32_16x16x32_bf16 v[2:5], v[172:175], v[204:207], v[2:5]
	v_mfma_f32_16x16x32_bf16 v[2:5], v[176:179], v[208:211], v[2:5]
	v_mfma_f32_16x16x32_bf16 v[6:9], v[164:167], v[204:207], v[6:9]
	v_mfma_f32_16x16x32_bf16 v[6:9], v[168:171], v[208:211], v[6:9]
	s_barrier
	s_setprio 0
	s_add_i32 s50, s50, 2
	s_add_u32 s26, s26, 0x100
	s_addc_u32 s27, s27, 0
	s_add_u32 s35, s35, 0x100
	s_addc_u32 s49, s49, 0
	s_cmp_gt_u32 s50, 29
	s_cbranch_scc0 .LBB0_924
	s_and_b64 vcc, exec, s[16:17]
	s_cbranch_vccz .LBB0_927
	s_barrier

; #define PG8_STAGE(bufoff, gbase, voff) do { _Pragma("unroll") for (int _i = 0; _i < 2; ++_i) \
;         __builtin_amdgcn_global_load_lds((const unsigned*)((const char*)(gbase) + (voff)[_i]), (LAS unsigned*)(lds + (bufoff) + ldsw + _i * 8192), 16, 0, 0); } while (0)
; #define PG8_LDA(dst, b, h) do { _Pragma("unroll") for (int m = 0; m < 4; ++m) _Pragma("unroll") for (int k = 0; k < 2; ++k) dst[m][k] = *(const LAS bf16x8*)(lds + PG8_SA(b, h) + aoff + m * 2048 + k * 1024); } while (0)
; #define PG8_LDB(dst, b, h) do { _Pragma("unroll") for (int n = 0; n < 2; ++n) _Pragma("unroll") for (int k = 0; k < 2; ++k) dst[n][k] = *(const LAS bf16x8*)(lds + PG8_SB(b, h) + boff + n * 2048 + k * 1024); } while (0)
; #define PG8_MMA(ai, bj, At, Bt) do { __builtin_amdgcn_s_setprio(1); _Pragma("unroll") for (int m = 0; m < 4; ++m) _Pragma("unroll") for (int n = 0; n < 2; ++n) _Pragma("unroll") for (int k = 0; k < 2; ++k) \
;         acc[ai][bj][m][n] = __builtin_amdgcn_mfma_f32_16x16x32_bf16(Bt[n][k], At[m][k], acc[ai][bj][m][n], 0, 0, 0); __builtin_amdgcn_s_setprio(0); } while (0)
; #define PG8_WAIT_V(n) asm volatile("s_waitcnt vmcnt(" #n ")" ::: "memory")
; #define PG8_WAIT_L(n) asm volatile("s_waitcnt lgkmcnt(" #n ")" ::: "memory")
; template <class Epi, class Sched, bool ALIGN_EPI = false, bool SP2 = false>
; __device__ __forceinline__ void gemm_phase(LAS unsigned char* lds, const Gemm g, const Sched& S, const Epi& E) {
;     ...
;         for (int t = 0; t < nt; t += 2) {
;             const bool last = (t == nt - 2);
;             const char* a1 = cA + (size_t)(t + 1) * kstep;
;             const char* a2 = last ? nA : cA + (size_t)(t + 2) * kstep; const char* b2 = last ? nB : cB + (size_t)(t + 2) * kstep;
;             const char* a3 = a2 + kstep; const char* b3 = b2 + kstep;
;             if (last && has_next) S.a_ready(nxt);
;             if constexpr (SP2) {
;             PG8_LDB(B0, 0, 0); PG8_LDB(B1, 0, 1); PG8_SCHED; PG8_LDA(At, 0, 0); PG8_STAGE(PG8_SA(1, 1), a1 + hstep, voffA);
;             PG8_WAIT_V(8); PG8_WAIT_L(0); PG8_BAR; PG8_MMA(0, 0, At, B0); PG8_MMA(0, 1, At, B1); PG8_BAR; PG8_SCHED;
;             PG8_LDA(At, 0, 1); PG8_STAGE(PG8_SB(0, 0), b2, voffB); PG8_STAGE(PG8_SB(0, 1), b2 + hstep, voffB); PG8_STAGE(PG8_SA(0, 0), a2, voffA);
;             PG8_WAIT_V(8); PG8_WAIT_L(0); PG8_BAR; PG8_MMA(1, 0, At, B0); PG8_MMA(1, 1, At, B1); PG8_BAR; PG8_SCHED;
.LBB0_1007:
	s_add_u32 s24, s22, 0x100
	s_addc_u32 s25, s23, 0
	s_add_i32 s49, 0, 0x10000
	s_cmpk_eq_i32 s48, 0x54
	s_cselect_b32 s29, s1, s25
	s_cselect_b32 s28, s0, s24
	s_cselect_b32 s27, s21, s47
	s_cselect_b32 s26, s20, s46
	s_add_i32 s50, 0, 0x14000
	v_add_u32_e32 v126, s49, v247
	v_add_u32_e32 v158, s50, v247
	ds_read_b128 v[90:93], v126
	ds_read_b128 v[102:105], v126 offset:1024
	ds_read_b128 v[114:117], v126 offset:2048
	ds_read_b128 v[126:129], v126 offset:3072
	ds_read_b128 v[138:141], v158
	ds_read_b128 v[142:145], v158 offset:1024
	ds_read_b128 v[154:157], v158 offset:2048
	ds_read_b128 v[158:161], v158 offset:3072
	v_lshl_add_u64 v[204:205], s[22:23], 0, v[200:201]
	s_add_i32 m0, s8, 0xc000
	ds_read_b128 v[162:165], v249
	ds_read_b128 v[166:169], v249 offset:1024
	ds_read_b128 v[170:173], v249 offset:2048
	ds_read_b128 v[174:177], v249 offset:3072
	ds_read_b128 v[178:181], v249 offset:4096
	ds_read_b128 v[182:185], v249 offset:5120
	ds_read_b128 v[186:189], v249 offset:6144
	ds_read_b128 v[190:193], v249 offset:7168
	global_load_lds_dwordx4 v[204:205], off
	v_lshl_add_u64 v[204:205], s[22:23], 0, v[202:203]
	s_add_i32 m0, s8, 0xe000
	s_nop 0
	global_load_lds_dwordx4 v[204:205], off
	s_waitcnt vmcnt(8)
	s_waitcnt lgkmcnt(0)
	s_setprio 1
	s_barrier
	v_mfma_f32_16x16x32_bf16 v[150:153], v[90:93], v[162:165], v[150:153]
	v_mfma_f32_16x16x32_bf16 v[150:153], v[102:105], v[166:169], v[150:153]
	v_mfma_f32_16x16x32_bf16 v[146:149], v[114:117], v[162:165], v[146:149]
	v_mfma_f32_16x16x32_bf16 v[146:149], v[126:129], v[166:169], v[146:149]
	v_mfma_f32_16x16x32_bf16 v[118:121], v[114:117], v[170:173], v[118:121]
	v_mfma_f32_16x16x32_bf16 v[118:121], v[126:129], v[174:177], v[118:121]
	v_mfma_f32_16x16x32_bf16 v[122:125], v[90:93], v[170:173], v[122:125]
	v_mfma_f32_16x16x32_bf16 v[122:125], v[102:105], v[174:177], v[122:125]
	v_mfma_f32_16x16x32_bf16 v[98:101], v[90:93], v[178:181], v[98:101]
	v_mfma_f32_16x16x32_bf16 v[98:101], v[102:105], v[182:185], v[98:101]
	v_mfma_f32_16x16x32_bf16 v[94:97], v[114:117], v[178:181], v[94:97]
	v_mfma_f32_16x16x32_bf16 v[94:97], v[126:129], v[182:185], v[94:97]
	v_mfma_f32_16x16x32_bf16 v[74:77], v[114:117], v[186:189], v[74:77]
	v_mfma_f32_16x16x32_bf16 v[74:77], v[126:129], v[190:193], v[74:77]
	v_mfma_f32_16x16x32_bf16 v[78:81], v[90:93], v[186:189], v[78:81]
	v_mfma_f32_16x16x32_bf16 v[78:81], v[102:105], v[190:193], v[78:81]
	v_mfma_f32_16x16x32_bf16 v[134:137], v[138:141], v[162:165], v[134:137]
	v_mfma_f32_16x16x32_bf16 v[134:137], v[142:145], v[166:169], v[134:137]
	v_mfma_f32_16x16x32_bf16 v[130:133], v[154:157], v[162:165], v[130:133]
	v_mfma_f32_16x16x32_bf16 v[130:133], v[158:161], v[166:169], v[130:133]
	v_mfma_f32_16x16x32_bf16 v[106:109], v[154:157], v[170:173], v[106:109]
	v_mfma_f32_16x16x32_bf16 v[106:109], v[158:161], v[174:177], v[106:109]
	v_mfma_f32_16x16x32_bf16 v[110:113], v[138:141], v[170:173], v[110:113]
	v_mfma_f32_16x16x32_bf16 v[110:113], v[142:145], v[174:177], v[110:113]
	v_mfma_f32_16x16x32_bf16 v[86:89], v[138:141], v[178:181], v[86:89]
	v_mfma_f32_16x16x32_bf16 v[86:89], v[142:145], v[182:185], v[86:89]
	v_mfma_f32_16x16x32_bf16 v[82:85], v[154:157], v[178:181], v[82:85]
	v_mfma_f32_16x16x32_bf16 v[82:85], v[158:161], v[182:185], v[82:85]
	v_mfma_f32_16x16x32_bf16 v[66:69], v[154:157], v[186:189], v[66:69]
	v_mfma_f32_16x16x32_bf16 v[66:69], v[158:161], v[190:193], v[66:69]
	v_mfma_f32_16x16x32_bf16 v[70:73], v[138:141], v[186:189], v[70:73]
	v_mfma_f32_16x16x32_bf16 v[70:73], v[142:145], v[190:193], v[70:73]
	s_barrier
	s_setprio 0
	s_add_i32 s22, s49, s7
	v_lshl_add_u64 v[204:205], s[26:27], 0, v[0:1]
	s_mov_b32 m0, s22
	ds_read_b128 v[162:165], v249 offset:16384
	ds_read_b128 v[166:169], v249 offset:17408
	ds_read_b128 v[170:173], v249 offset:18432
	ds_read_b128 v[174:177], v249 offset:19456
	ds_read_b128 v[178:181], v249 offset:20480
	ds_read_b128 v[182:185], v249 offset:21504
	ds_read_b128 v[186:189], v249 offset:22528
	ds_read_b128 v[190:193], v249 offset:23552
	global_load_lds_dwordx4 v[204:205], off
	s_add_i32 m0, s22, 0x2000
	s_add_u32 s22, s26, 0x160000
	v_lshl_add_u64 v[206:207], s[26:27], 0, v[194:195]
	s_addc_u32 s23, s27, 0
	s_add_i32 s49, s50, s7
	global_load_lds_dwordx4 v[206:207], off
	v_lshl_add_u64 v[208:209], s[22:23], 0, v[0:1]
	s_mov_b32 m0, s49
	v_lshl_add_u64 v[210:211], s[28:29], 0, v[196:197]
	global_load_lds_dwordx4 v[208:209], off
	v_lshl_add_u64 v[208:209], s[22:23], 0, v[194:195]
	s_add_i32 m0, s49, 0x2000
	s_nop 0
	global_load_lds_dwordx4 v[208:209], off
	v_lshl_add_u64 v[208:209], s[28:29], 0, v[198:199]
	s_mov_b32 m0, s8
	s_nop 0
	global_load_lds_dwordx4 v[208:209], off
	s_mov_b32 m0, s9
	s_nop 0
	global_load_lds_dwordx4 v[210:211], off
	s_waitcnt vmcnt(8)
	s_waitcnt lgkmcnt(0)
	s_setprio 1
	s_barrier
; #define PG8_STAGE(bufoff, gbase, voff) do { _Pragma("unroll") for (int _i = 0; _i < 2; ++_i) \
;         __builtin_amdgcn_global_load_lds((const unsigned*)((const char*)(gbase) + (voff)[_i]), (LAS unsigned*)(lds + (bufoff) + ldsw + _i * 8192), 16, 0, 0); } while (0)
; #define PG8_LDA(dst, b, h) do { _Pragma("unroll") for (int m = 0; m < 4; ++m) _Pragma("unroll") for (int k = 0; k < 2; ++k) dst[m][k] = *(const LAS bf16x8*)(lds + PG8_SA(b, h) + aoff + m * 2048 + k * 1024); } while (0)
; #define PG8_LDB(dst, b, h) do { _Pragma("unroll") for (int n = 0; n < 2; ++n) _Pragma("unroll") for (int k = 0; k < 2; ++k) dst[n][k] = *(const LAS bf16x8*)(lds + PG8_SB(b, h) + boff + n * 2048 + k * 1024); } while (0)
; #define PG8_MMA(ai, bj, At, Bt) do { __builtin_amdgcn_s_setprio(1); _Pragma("unroll") for (int m = 0; m < 4; ++m) _Pragma("unroll") for (int n = 0; n < 2; ++n) _Pragma("unroll") for (int k = 0; k < 2; ++k) \
;         acc[ai][bj][m][n] = __builtin_amdgcn_mfma_f32_16x16x32_bf16(Bt[n][k], At[m][k], acc[ai][bj][m][n], 0, 0, 0); __builtin_amdgcn_s_setprio(0); } while (0)
; #define PG8_WAIT_V(n) asm volatile("s_waitcnt vmcnt(" #n ")" ::: "memory")
; #define PG8_WAIT_L(n) asm volatile("s_waitcnt lgkmcnt(" #n ")" ::: "memory")
; #define PG8_BAR __builtin_amdgcn_s_barrier()
; #define PG8_SCHED __builtin_amdgcn_sched_barrier(0)
; template <class Epi, class Sched, bool ALIGN_EPI = false, bool SP2 = false>
; __device__ __forceinline__ void gemm_phase(LAS unsigned char* lds, const Gemm g, const Sched& S, const Epi& E) {
;     ...
;             PG8_WAIT_V(8); PG8_WAIT_L(0); PG8_BAR; PG8_MMA(1, 0, At, B0); PG8_MMA(1, 1, At, B1); PG8_BAR; PG8_SCHED;
;             PG8_LDB(B0, 1, 0); PG8_LDB(B1, 1, 1); PG8_SCHED; PG8_LDA(At, 1, 0); PG8_STAGE(PG8_SA(0, 1), a2 + hstep, voffA);
;             PG8_WAIT_V(8); PG8_WAIT_L(0); PG8_BAR; PG8_MMA(0, 0, At, B0); PG8_MMA(0, 1, At, B1); PG8_BAR; PG8_SCHED;
	v_mfma_f32_16x16x32_bf16 v[62:65], v[90:93], v[162:165], v[62:65]
	v_mfma_f32_16x16x32_bf16 v[62:65], v[102:105], v[166:169], v[62:65]
	v_mfma_f32_16x16x32_bf16 v[58:61], v[114:117], v[162:165], v[58:61]
	v_mfma_f32_16x16x32_bf16 v[58:61], v[126:129], v[166:169], v[58:61]
	v_mfma_f32_16x16x32_bf16 v[42:45], v[114:117], v[170:173], v[42:45]
	v_mfma_f32_16x16x32_bf16 v[42:45], v[126:129], v[174:177], v[42:45]
	v_mfma_f32_16x16x32_bf16 v[46:49], v[90:93], v[170:173], v[46:49]
	v_mfma_f32_16x16x32_bf16 v[46:49], v[102:105], v[174:177], v[46:49]
	v_mfma_f32_16x16x32_bf16 v[30:33], v[90:93], v[178:181], v[30:33]
	v_mfma_f32_16x16x32_bf16 v[30:33], v[102:105], v[182:185], v[30:33]
	v_mfma_f32_16x16x32_bf16 v[26:29], v[114:117], v[178:181], v[26:29]
	v_mfma_f32_16x16x32_bf16 v[26:29], v[126:129], v[182:185], v[26:29]
	v_mfma_f32_16x16x32_bf16 v[10:13], v[114:117], v[186:189], v[10:13]
	v_mfma_f32_16x16x32_bf16 v[10:13], v[126:129], v[190:193], v[10:13]
	v_mfma_f32_16x16x32_bf16 v[14:17], v[90:93], v[186:189], v[14:17]
	v_mfma_f32_16x16x32_bf16 v[14:17], v[102:105], v[190:193], v[14:17]
	v_mfma_f32_16x16x32_bf16 v[54:57], v[138:141], v[162:165], v[54:57]
	v_mfma_f32_16x16x32_bf16 v[54:57], v[142:145], v[166:169], v[54:57]
	v_mfma_f32_16x16x32_bf16 v[50:53], v[154:157], v[162:165], v[50:53]
	v_mfma_f32_16x16x32_bf16 v[50:53], v[158:161], v[166:169], v[50:53]
	v_mfma_f32_16x16x32_bf16 v[34:37], v[154:157], v[170:173], v[34:37]
	v_mfma_f32_16x16x32_bf16 v[34:37], v[158:161], v[174:177], v[34:37]
	v_mfma_f32_16x16x32_bf16 v[38:41], v[138:141], v[170:173], v[38:41]
	v_mfma_f32_16x16x32_bf16 v[38:41], v[142:145], v[174:177], v[38:41]
	v_mfma_f32_16x16x32_bf16 v[22:25], v[138:141], v[178:181], v[22:25]
	v_mfma_f32_16x16x32_bf16 v[22:25], v[142:145], v[182:185], v[22:25]
	v_mfma_f32_16x16x32_bf16 v[18:21], v[154:157], v[178:181], v[18:21]
	v_mfma_f32_16x16x32_bf16 v[18:21], v[158:161], v[182:185], v[18:21]
	v_mfma_f32_16x16x32_bf16 v[2:5], v[154:157], v[186:189], v[2:5]
	v_mfma_f32_16x16x32_bf16 v[2:5], v[158:161], v[190:193], v[2:5]
	v_mfma_f32_16x16x32_bf16 v[6:9], v[138:141], v[186:189], v[6:9]
	v_mfma_f32_16x16x32_bf16 v[6:9], v[142:145], v[190:193], v[6:9]
	s_barrier
	s_setprio 0
	s_add_i32 s49, 0, 0x18000
	s_add_i32 s50, 0, 0x1c000
	v_add_u32_e32 v126, s49, v247
	v_add_u32_e32 v158, s50, v247
	ds_read_b128 v[90:93], v126
	ds_read_b128 v[102:105], v126 offset:1024
	ds_read_b128 v[114:117], v126 offset:2048
	ds_read_b128 v[126:129], v126 offset:3072
	ds_read_b128 v[138:141], v158
	ds_read_b128 v[142:145], v158 offset:1024
	ds_read_b128 v[154:157], v158 offset:2048
	ds_read_b128 v[158:161], v158 offset:3072
	s_add_u32 s22, s28, 0x160000
	s_addc_u32 s23, s29, 0
	s_mov_b32 m0, s30
	v_lshl_add_u64 v[212:213], s[22:23], 0, v[198:199]
	ds_read_b128 v[162:165], v249 offset:32768
	ds_read_b128 v[166:169], v249 offset:33792
	ds_read_b128 v[170:173], v249 offset:34816
	ds_read_b128 v[174:177], v249 offset:35840
	ds_read_b128 v[178:181], v249 offset:36864
	ds_read_b128 v[182:185], v249 offset:37888
	ds_read_b128 v[186:189], v249 offset:38912
	ds_read_b128 v[190:193], v249 offset:39936
	global_load_lds_dwordx4 v[212:213], off
	v_lshl_add_u64 v[212:213], s[22:23], 0, v[196:197]
	s_mov_b32 m0, s31
	s_nop 0
	global_load_lds_dwordx4 v[212:213], off
	s_waitcnt vmcnt(8)
	s_waitcnt lgkmcnt(0)
	s_setprio 1
	s_barrier
	v_mfma_f32_16x16x32_bf16 v[150:153], v[90:93], v[162:165], v[150:153]
	v_mfma_f32_16x16x32_bf16 v[150:153], v[102:105], v[166:169], v[150:153]
	v_mfma_f32_16x16x32_bf16 v[146:149], v[114:117], v[162:165], v[146:149]
	v_mfma_f32_16x16x32_bf16 v[146:149], v[126:129], v[166:169], v[146:149]
	v_mfma_f32_16x16x32_bf16 v[118:121], v[114:117], v[170:173], v[118:121]
	v_mfma_f32_16x16x32_bf16 v[118:121], v[126:129], v[174:177], v[118:121]
	v_mfma_f32_16x16x32_bf16 v[122:125], v[90:93], v[170:173], v[122:125]
	v_mfma_f32_16x16x32_bf16 v[122:125], v[102:105], v[174:177], v[122:125]
	v_mfma_f32_16x16x32_bf16 v[98:101], v[90:93], v[178:181], v[98:101]
	v_mfma_f32_16x16x32_bf16 v[98:101], v[102:105], v[182:185], v[98:101]
	v_mfma_f32_16x16x32_bf16 v[94:97], v[114:117], v[178:181], v[94:97]
	v_mfma_f32_16x16x32_bf16 v[94:97], v[126:129], v[182:185], v[94:97]
	v_mfma_f32_16x16x32_bf16 v[74:77], v[114:117], v[186:189], v[74:77]
	v_mfma_f32_16x16x32_bf16 v[74:77], v[126:129], v[190:193], v[74:77]
	v_mfma_f32_16x16x32_bf16 v[78:81], v[90:93], v[186:189], v[78:81]
	v_mfma_f32_16x16x32_bf16 v[78:81], v[102:105], v[190:193], v[78:81]
	v_mfma_f32_16x16x32_bf16 v[134:137], v[138:141], v[162:165], v[134:137]
	v_mfma_f32_16x16x32_bf16 v[134:137], v[142:145], v[166:169], v[134:137]
	v_mfma_f32_16x16x32_bf16 v[130:133], v[154:157], v[162:165], v[130:133]
	v_mfma_f32_16x16x32_bf16 v[130:133], v[158:161], v[166:169], v[130:133]
	v_mfma_f32_16x16x32_bf16 v[106:109], v[154:157], v[170:173], v[106:109]
	v_mfma_f32_16x16x32_bf16 v[106:109], v[158:161], v[174:177], v[106:109]
	v_mfma_f32_16x16x32_bf16 v[110:113], v[138:141], v[170:173], v[110:113]
	v_mfma_f32_16x16x32_bf16 v[110:113], v[142:145], v[174:177], v[110:113]
	v_mfma_f32_16x16x32_bf16 v[86:89], v[138:141], v[178:181], v[86:89]
	v_mfma_f32_16x16x32_bf16 v[86:89], v[142:145], v[182:185], v[86:89]
	v_mfma_f32_16x16x32_bf16 v[82:85], v[154:157], v[178:181], v[82:85]
	v_mfma_f32_16x16x32_bf16 v[82:85], v[158:161], v[182:185], v[82:85]
	v_mfma_f32_16x16x32_bf16 v[66:69], v[154:157], v[186:189], v[66:69]
	v_mfma_f32_16x16x32_bf16 v[66:69], v[158:161], v[190:193], v[66:69]
	v_mfma_f32_16x16x32_bf16 v[70:73], v[138:141], v[186:189], v[70:73]
	v_mfma_f32_16x16x32_bf16 v[70:73], v[142:145], v[190:193], v[70:73]
	s_barrier
; #define PG8_STAGE(bufoff, gbase, voff) do { _Pragma("unroll") for (int _i = 0; _i < 2; ++_i) \
;         __builtin_amdgcn_global_load_lds((const unsigned*)((const char*)(gbase) + (voff)[_i]), (LAS unsigned*)(lds + (bufoff) + ldsw + _i * 8192), 16, 0, 0); } while (0)
; #define PG8_LDA(dst, b, h) do { _Pragma("unroll") for (int m = 0; m < 4; ++m) _Pragma("unroll") for (int k = 0; k < 2; ++k) dst[m][k] = *(const LAS bf16x8*)(lds + PG8_SA(b, h) + aoff + m * 2048 + k * 1024); } while (0)
; #define PG8_MMA(ai, bj, At, Bt) do { __builtin_amdgcn_s_setprio(1); _Pragma("unroll") for (int m = 0; m < 4; ++m) _Pragma("unroll") for (int n = 0; n < 2; ++n) _Pragma("unroll") for (int k = 0; k < 2; ++k) \
;         acc[ai][bj][m][n] = __builtin_amdgcn_mfma_f32_16x16x32_bf16(Bt[n][k], At[m][k], acc[ai][bj][m][n], 0, 0, 0); __builtin_amdgcn_s_setprio(0); } while (0)
; #define PG8_WAIT_V(n) asm volatile("s_waitcnt vmcnt(" #n ")" ::: "memory")
; #define PG8_WAIT_L(n) asm volatile("s_waitcnt lgkmcnt(" #n ")" ::: "memory")
; #define PG8_BAR __builtin_amdgcn_s_barrier()
; #define PG8_SCHED __builtin_amdgcn_sched_barrier(0)
; template <class Epi, class Sched, bool ALIGN_EPI = false, bool SP2 = false>
; __device__ __forceinline__ void gemm_phase(LAS unsigned char* lds, const Gemm g, const Sched& S, const Epi& E) {
;     ...
;         for (int t = 0; t < nt; t += 2) {
;             const bool last = (t == nt - 2);
;             const char* a1 = cA + (size_t)(t + 1) * kstep;
;             const char* a2 = last ? nA : cA + (size_t)(t + 2) * kstep; const char* b2 = last ? nB : cB + (size_t)(t + 2) * kstep;
;             const char* a3 = a2 + kstep; const char* b3 = b2 + kstep;
;             if (last && has_next) S.a_ready(nxt);
;     ...
;             PG8_WAIT_V(8); PG8_WAIT_L(0); PG8_BAR; PG8_MMA(0, 0, At, B0); PG8_MMA(0, 1, At, B1); PG8_BAR; PG8_SCHED;
;             PG8_LDA(At, 1, 1); PG8_STAGE(PG8_SB(1, 0), b3, voffB); PG8_STAGE(PG8_SB(1, 1), b3 + hstep, voffB); PG8_STAGE(PG8_SA(1, 0), a3, voffA);
;             PG8_WAIT_V(8); PG8_WAIT_L(0); PG8_BAR; PG8_MMA(1, 0, At, B0); PG8_MMA(1, 1, At, B1); PG8_BAR; PG8_SCHED;
	s_setprio 0
	s_add_i32 s22, s49, s7
	v_lshl_add_u64 v[204:205], v[204:205], 0, s[12:13]
	s_mov_b32 m0, s22
	ds_read_b128 v[162:165], v249 offset:49152
	ds_read_b128 v[166:169], v249 offset:50176
	ds_read_b128 v[170:173], v249 offset:51200
	ds_read_b128 v[174:177], v249 offset:52224
	ds_read_b128 v[178:181], v249 offset:53248
	ds_read_b128 v[182:185], v249 offset:54272
	ds_read_b128 v[186:189], v249 offset:55296
	ds_read_b128 v[190:193], v249 offset:56320
	global_load_lds_dwordx4 v[204:205], off
	s_add_i32 m0, s22, 0x2000
	s_add_u32 s22, s26, 0x160080
	v_lshl_add_u64 v[204:205], v[206:207], 0, s[12:13]
	s_addc_u32 s23, s27, 0
	s_add_i32 s26, s50, s7
	global_load_lds_dwordx4 v[204:205], off
	v_lshl_add_u64 v[204:205], s[22:23], 0, v[0:1]
	s_mov_b32 m0, s26
	s_nop 0
	global_load_lds_dwordx4 v[204:205], off
	v_lshl_add_u64 v[204:205], s[22:23], 0, v[194:195]
	s_add_i32 m0, s26, 0x2000
	s_nop 0
	global_load_lds_dwordx4 v[204:205], off
	v_lshl_add_u64 v[204:205], v[208:209], 0, s[12:13]
	s_mov_b32 m0, s35
	s_nop 0
	global_load_lds_dwordx4 v[204:205], off
	v_lshl_add_u64 v[204:205], v[210:211], 0, s[12:13]
	s_mov_b32 m0, s40
	s_nop 0
	global_load_lds_dwordx4 v[204:205], off
	s_waitcnt vmcnt(8)
	s_waitcnt lgkmcnt(0)
	s_setprio 1
	s_barrier
	v_mfma_f32_16x16x32_bf16 v[62:65], v[90:93], v[162:165], v[62:65]
	v_mfma_f32_16x16x32_bf16 v[62:65], v[102:105], v[166:169], v[62:65]
	v_mfma_f32_16x16x32_bf16 v[58:61], v[114:117], v[162:165], v[58:61]
	v_mfma_f32_16x16x32_bf16 v[58:61], v[126:129], v[166:169], v[58:61]
	v_mfma_f32_16x16x32_bf16 v[42:45], v[114:117], v[170:173], v[42:45]
	v_mfma_f32_16x16x32_bf16 v[42:45], v[126:129], v[174:177], v[42:45]
	v_mfma_f32_16x16x32_bf16 v[46:49], v[90:93], v[170:173], v[46:49]
	v_mfma_f32_16x16x32_bf16 v[46:49], v[102:105], v[174:177], v[46:49]
	v_mfma_f32_16x16x32_bf16 v[30:33], v[90:93], v[178:181], v[30:33]
	v_mfma_f32_16x16x32_bf16 v[30:33], v[102:105], v[182:185], v[30:33]
	v_mfma_f32_16x16x32_bf16 v[26:29], v[114:117], v[178:181], v[26:29]
	v_mfma_f32_16x16x32_bf16 v[26:29], v[126:129], v[182:185], v[26:29]
	v_mfma_f32_16x16x32_bf16 v[10:13], v[114:117], v[186:189], v[10:13]
	v_mfma_f32_16x16x32_bf16 v[10:13], v[126:129], v[190:193], v[10:13]
	v_mfma_f32_16x16x32_bf16 v[14:17], v[90:93], v[186:189], v[14:17]
	v_mfma_f32_16x16x32_bf16 v[14:17], v[102:105], v[190:193], v[14:17]
	v_mfma_f32_16x16x32_bf16 v[54:57], v[138:141], v[162:165], v[54:57]
	v_mfma_f32_16x16x32_bf16 v[54:57], v[142:145], v[166:169], v[54:57]
	v_mfma_f32_16x16x32_bf16 v[50:53], v[154:157], v[162:165], v[50:53]
	v_mfma_f32_16x16x32_bf16 v[50:53], v[158:161], v[166:169], v[50:53]
	v_mfma_f32_16x16x32_bf16 v[34:37], v[154:157], v[170:173], v[34:37]
	v_mfma_f32_16x16x32_bf16 v[34:37], v[158:161], v[174:177], v[34:37]
	v_mfma_f32_16x16x32_bf16 v[38:41], v[138:141], v[170:173], v[38:41]
	v_mfma_f32_16x16x32_bf16 v[38:41], v[142:145], v[174:177], v[38:41]
	v_mfma_f32_16x16x32_bf16 v[22:25], v[138:141], v[178:181], v[22:25]
	v_mfma_f32_16x16x32_bf16 v[22:25], v[142:145], v[182:185], v[22:25]
	v_mfma_f32_16x16x32_bf16 v[18:21], v[154:157], v[178:181], v[18:21]
	v_mfma_f32_16x16x32_bf16 v[18:21], v[158:161], v[182:185], v[18:21]
	v_mfma_f32_16x16x32_bf16 v[2:5], v[154:157], v[186:189], v[2:5]
	v_mfma_f32_16x16x32_bf16 v[2:5], v[158:161], v[190:193], v[2:5]
	v_mfma_f32_16x16x32_bf16 v[6:9], v[138:141], v[186:189], v[6:9]
	v_mfma_f32_16x16x32_bf16 v[6:9], v[142:145], v[190:193], v[6:9]
	s_barrier
	s_setprio 0
	s_add_i32 s48, s48, 2
	s_add_u32 s46, s46, 0x100
	s_addc_u32 s47, s47, 0
	s_cmpk_gt_u32 s48, 0x55
	s_mov_b64 s[22:23], s[24:25]
	s_cbranch_scc0 .LBB0_1007
	s_and_b64 vcc, exec, s[18:19]
	s_cbranch_vccz .LBB0_1010
	s_barrier
